# GEMM K-loops: LDS-DMA requests in saddr form (SGPR base + 32-bit VGPR offset), 62 v_lshl_add_u64 per iteration set removed from the load phases; K-step bases by SALU
# speedup vs baseline: 1.0018x; 1.0018x over previous
; #define PG8_STAGE(bufoff, gbase, voff) do { _Pragma("unroll") for (int _i = 0; _i < 2; ++_i) \
;         __builtin_amdgcn_global_load_lds((const unsigned*)((const char*)(gbase) + (voff)[_i]), (PG8_LAS unsigned*)(lds + (bufoff) + ldsw + _i * 8192), 16, 0, 0); } while (0)
; #define PG8_LDA(dst, b, h) do { _Pragma("unroll") for (int m = 0; m < 4; ++m) _Pragma("unroll") for (int k = 0; k < 2; ++k) dst[m][k] = *(const PG8_LAS bf16x8*)(lds + PG8_SA(b, h) + aoff + m * 2048 + k * 1024); } while (0)
; #define PG8_LDB(dst, b, h) do { _Pragma("unroll") for (int n = 0; n < 2; ++n) _Pragma("unroll") for (int k = 0; k < 2; ++k) dst[n][k] = *(const PG8_LAS bf16x8*)(lds + PG8_SB(b, h) + boff + n * 2048 + k * 1024); } while (0)
; #define PG8_MMA(ai, bj, At, Bt) do { __builtin_amdgcn_s_setprio(1); _Pragma("unroll") for (int m = 0; m < 4; ++m) _Pragma("unroll") for (int n = 0; n < 2; ++n) _Pragma("unroll") for (int k = 0; k < 2; ++k) \
;         acc[ai][bj][m][n] = __builtin_amdgcn_mfma_f32_16x16x32_bf16(Bt[n][k], At[m][k], acc[ai][bj][m][n], 0, 0, 0); __builtin_amdgcn_s_setprio(0); } while (0)
; #define PG8_WAIT_V(n) asm volatile("s_waitcnt vmcnt(" #n ")" ::: "memory")
; #define PG8_WAIT_L(n) asm volatile("s_waitcnt lgkmcnt(" #n ")" ::: "memory")
; #define PG8_BAR __builtin_amdgcn_s_barrier()
; #define PG8_SCHED __builtin_amdgcn_sched_barrier(0)
; template <class Epi, class Sched, bool ALIGN_EPI = false, bool SP2 = false>
; __device__ __forceinline__ void gemm_phase(PG8_LAS unsigned char* lds, const Gemm g, const Sched& S, const Epi& E) {
;     ...
;             const bool last = (t == nt - 2);
;             const char* a1 = cA + (size_t)(t + 1) * kstep;
;             const char* a2 = last ? nA : cA + (size_t)(t + 2) * kstep; const char* b2 = last ? nB : cB + (size_t)(t + 2) * kstep;
;             const char* a3 = a2 + kstep; const char* b3 = b2 + kstep;
;             if (last && has_next) S.a_ready(nxt);
;             if constexpr (SP2) {
;             PG8_LDB(B0, 0, 0); PG8_LDB(B1, 0, 1); PG8_SCHED; PG8_LDA(At, 0, 0); PG8_STAGE(PG8_SA(1, 1), a1 + hstep, voffA);
;             PG8_WAIT_V(8); PG8_WAIT_L(0); PG8_BAR; PG8_MMA(0, 0, At, B0); PG8_MMA(0, 1, At, B1); PG8_BAR; PG8_SCHED;
;             PG8_LDA(At, 0, 1); PG8_STAGE(PG8_SB(0, 0), b2, voffB); PG8_STAGE(PG8_SB(0, 1), b2 + hstep, voffB); PG8_STAGE(PG8_SA(0, 0), a2, voffA);
.LBB0_121:
	s_add_u32 s46, s44, 0xfffc0080
	s_addc_u32 s47, s45, -1
	s_add_i32 s64, 0, 0x10000
	s_cmp_eq_u32 s63, 12
	s_cselect_b32 s49, s41, s47
	s_cselect_b32 s48, s40, s46
	v_add_u32_e32 v146, s64, v149
	s_cselect_b32 s47, s37, s62
	s_cselect_b32 s46, s39, s61
	s_add_i32 s67, 0, 0x14000
	ds_read_b128 v[152:155], v146
	ds_read_b128 v[156:159], v146 offset:1024
	ds_read_b128 v[160:163], v146 offset:2048
	ds_read_b128 v[174:177], v146 offset:3072
	v_add_u32_e32 v146, s67, v149
	ds_read_b128 v[178:181], v146
	ds_read_b128 v[182:185], v146 offset:1024
	ds_read_b128 v[186:189], v146 offset:2048
	ds_read_b128 v[190:193], v146 offset:3072
	s_add_i32 m0, s52, 0xc000
	ds_read_b128 v[194:197], v151
	ds_read_b128 v[198:201], v151 offset:1024
	ds_read_b128 v[202:205], v151 offset:2048
	ds_read_b128 v[206:209], v151 offset:3072
	ds_read_b128 v[210:213], v151 offset:4096
	ds_read_b128 v[214:217], v151 offset:5120
	ds_read_b128 v[218:221], v151 offset:6144
	ds_read_b128 v[222:225], v151 offset:7168
	global_load_lds_dwordx4 v142, s[44:45]
	s_add_i32 m0, s52, 0xe000
	s_nop 0
	global_load_lds_dwordx4 v144, s[44:45]
	s_waitcnt vmcnt(8)
	s_waitcnt lgkmcnt(0)
	s_barrier
	s_setprio 1
	s_waitcnt lgkmcnt(0)
	v_mfma_f32_16x16x32_bf16 v[126:129], v[152:155], v[194:197], v[126:129]
	v_mfma_f32_16x16x32_bf16 v[122:125], v[160:163], v[194:197], v[122:125]
	v_mfma_f32_16x16x32_bf16 v[118:121], v[152:155], v[202:205], v[118:121]
	v_mfma_f32_16x16x32_bf16 v[110:113], v[160:163], v[202:205], v[110:113]
	v_mfma_f32_16x16x32_bf16 v[102:105], v[152:155], v[210:213], v[102:105]
	v_mfma_f32_16x16x32_bf16 v[94:97], v[160:163], v[210:213], v[94:97]
	v_mfma_f32_16x16x32_bf16 v[86:89], v[152:155], v[218:221], v[86:89]
	v_mfma_f32_16x16x32_bf16 v[78:81], v[160:163], v[218:221], v[78:81]
	v_mfma_f32_16x16x32_bf16 v[126:129], v[156:159], v[198:201], v[126:129]
	v_mfma_f32_16x16x32_bf16 v[122:125], v[174:177], v[198:201], v[122:125]
	v_mfma_f32_16x16x32_bf16 v[118:121], v[156:159], v[206:209], v[118:121]
	v_mfma_f32_16x16x32_bf16 v[110:113], v[174:177], v[206:209], v[110:113]
	v_mfma_f32_16x16x32_bf16 v[102:105], v[156:159], v[214:217], v[102:105]
	v_mfma_f32_16x16x32_bf16 v[94:97], v[174:177], v[214:217], v[94:97]
	v_mfma_f32_16x16x32_bf16 v[86:89], v[156:159], v[222:225], v[86:89]
	v_mfma_f32_16x16x32_bf16 v[78:81], v[174:177], v[222:225], v[78:81]
	s_setprio 0
	s_setprio 1
	v_mfma_f32_16x16x32_bf16 v[114:117], v[178:181], v[194:197], v[114:117]
	v_mfma_f32_16x16x32_bf16 v[106:109], v[186:189], v[194:197], v[106:109]
	v_mfma_f32_16x16x32_bf16 v[98:101], v[178:181], v[202:205], v[98:101]
	v_mfma_f32_16x16x32_bf16 v[90:93], v[186:189], v[202:205], v[90:93]
	v_mfma_f32_16x16x32_bf16 v[82:85], v[178:181], v[210:213], v[82:85]
	v_mfma_f32_16x16x32_bf16 v[74:77], v[186:189], v[210:213], v[74:77]
	v_mfma_f32_16x16x32_bf16 v[70:73], v[178:181], v[218:221], v[70:73]
	v_mfma_f32_16x16x32_bf16 v[66:69], v[186:189], v[218:221], v[66:69]
	v_mfma_f32_16x16x32_bf16 v[114:117], v[182:185], v[198:201], v[114:117]
	v_mfma_f32_16x16x32_bf16 v[106:109], v[190:193], v[198:201], v[106:109]
	v_mfma_f32_16x16x32_bf16 v[98:101], v[182:185], v[206:209], v[98:101]
	v_mfma_f32_16x16x32_bf16 v[90:93], v[190:193], v[206:209], v[90:93]
	v_mfma_f32_16x16x32_bf16 v[82:85], v[182:185], v[214:217], v[82:85]
	v_mfma_f32_16x16x32_bf16 v[74:77], v[190:193], v[214:217], v[74:77]
	v_mfma_f32_16x16x32_bf16 v[70:73], v[182:185], v[222:225], v[70:73]
	s_barrier
	v_mfma_f32_16x16x32_bf16 v[66:69], v[190:193], v[222:225], v[66:69]
	s_setprio 0
	s_add_i32 s64, s64, s34
	s_add_u32 s98, s46, s96
	s_addc_u32 s99, s47, s97
	s_mov_b32 m0, s64
	ds_read_b128 v[194:197], v151 offset:16384
	ds_read_b128 v[198:201], v151 offset:17408
	ds_read_b128 v[202:205], v151 offset:18432
	ds_read_b128 v[206:209], v151 offset:19456
	ds_read_b128 v[210:213], v151 offset:20480
	ds_read_b128 v[214:217], v151 offset:21504
	ds_read_b128 v[218:221], v151 offset:22528
	ds_read_b128 v[222:225], v151 offset:23552
	global_load_lds_dwordx4 v130, s[46:47]
	s_add_i32 m0, s64, 0x2000
	s_add_u32 s64, s46, 0x40000
	s_addc_u32 s65, s47, 0
	s_add_i32 s67, s67, s34
	global_load_lds_dwordx4 v136, s[46:47]
	s_mov_b32 m0, s67
	s_nop 0
	global_load_lds_dwordx4 v130, s[64:65]
	s_add_i32 m0, s67, 0x2000
	s_nop 0
	global_load_lds_dwordx4 v136, s[64:65]
	s_add_u32 s100, s48, s96
	s_addc_u32 s101, s49, s97
	s_mov_b32 m0, s52
	s_nop 0
	global_load_lds_dwordx4 v140, s[48:49]
	s_mov_b32 m0, s53
	s_nop 0
	global_load_lds_dwordx4 v138, s[48:49]
	s_waitcnt vmcnt(8)
	s_waitcnt lgkmcnt(0)
	s_barrier
; #define PG8_STAGE(bufoff, gbase, voff) do { _Pragma("unroll") for (int _i = 0; _i < 2; ++_i) \
;         __builtin_amdgcn_global_load_lds((const unsigned*)((const char*)(gbase) + (voff)[_i]), (PG8_LAS unsigned*)(lds + (bufoff) + ldsw + _i * 8192), 16, 0, 0); } while (0)
; #define PG8_LDA(dst, b, h) do { _Pragma("unroll") for (int m = 0; m < 4; ++m) _Pragma("unroll") for (int k = 0; k < 2; ++k) dst[m][k] = *(const PG8_LAS bf16x8*)(lds + PG8_SA(b, h) + aoff + m * 2048 + k * 1024); } while (0)
; #define PG8_LDB(dst, b, h) do { _Pragma("unroll") for (int n = 0; n < 2; ++n) _Pragma("unroll") for (int k = 0; k < 2; ++k) dst[n][k] = *(const PG8_LAS bf16x8*)(lds + PG8_SB(b, h) + boff + n * 2048 + k * 1024); } while (0)
; #define PG8_MMA(ai, bj, At, Bt) do { __builtin_amdgcn_s_setprio(1); _Pragma("unroll") for (int m = 0; m < 4; ++m) _Pragma("unroll") for (int n = 0; n < 2; ++n) _Pragma("unroll") for (int k = 0; k < 2; ++k) \
;         acc[ai][bj][m][n] = __builtin_amdgcn_mfma_f32_16x16x32_bf16(Bt[n][k], At[m][k], acc[ai][bj][m][n], 0, 0, 0); __builtin_amdgcn_s_setprio(0); } while (0)
; #define PG8_WAIT_V(n) asm volatile("s_waitcnt vmcnt(" #n ")" ::: "memory")
; #define PG8_WAIT_L(n) asm volatile("s_waitcnt lgkmcnt(" #n ")" ::: "memory")
; #define PG8_BAR __builtin_amdgcn_s_barrier()
; #define PG8_SCHED __builtin_amdgcn_sched_barrier(0)
; template <class Epi, class Sched, bool ALIGN_EPI = false, bool SP2 = false>
; __device__ __forceinline__ void gemm_phase(PG8_LAS unsigned char* lds, const Gemm g, const Sched& S, const Epi& E) {
;     ...
;             PG8_WAIT_V(8); PG8_WAIT_L(0); PG8_BAR; PG8_MMA(1, 0, At, B0); PG8_MMA(1, 1, At, B1); PG8_BAR; PG8_SCHED;
;             PG8_LDB(B0, 1, 0); PG8_LDB(B1, 1, 1); PG8_SCHED; PG8_LDA(At, 1, 0); PG8_STAGE(PG8_SA(0, 1), a2 + hstep, voffA);
;             PG8_WAIT_V(8); PG8_WAIT_L(0); PG8_BAR; PG8_MMA(0, 0, At, B0); PG8_MMA(0, 1, At, B1); PG8_BAR; PG8_SCHED;
	s_setprio 1
	s_waitcnt lgkmcnt(0)
	v_mfma_f32_16x16x32_bf16 v[62:65], v[152:155], v[194:197], v[62:65]
	v_mfma_f32_16x16x32_bf16 v[58:61], v[160:163], v[194:197], v[58:61]
	v_mfma_f32_16x16x32_bf16 v[54:57], v[152:155], v[202:205], v[54:57]
	v_mfma_f32_16x16x32_bf16 v[46:49], v[160:163], v[202:205], v[46:49]
	v_mfma_f32_16x16x32_bf16 v[38:41], v[152:155], v[210:213], v[38:41]
	v_mfma_f32_16x16x32_bf16 v[30:33], v[160:163], v[210:213], v[30:33]
	v_mfma_f32_16x16x32_bf16 v[22:25], v[152:155], v[218:221], v[22:25]
	v_mfma_f32_16x16x32_bf16 v[14:17], v[160:163], v[218:221], v[14:17]
	v_mfma_f32_16x16x32_bf16 v[62:65], v[156:159], v[198:201], v[62:65]
	v_mfma_f32_16x16x32_bf16 v[58:61], v[174:177], v[198:201], v[58:61]
	v_mfma_f32_16x16x32_bf16 v[54:57], v[156:159], v[206:209], v[54:57]
	v_mfma_f32_16x16x32_bf16 v[46:49], v[174:177], v[206:209], v[46:49]
	v_mfma_f32_16x16x32_bf16 v[38:41], v[156:159], v[214:217], v[38:41]
	v_mfma_f32_16x16x32_bf16 v[30:33], v[174:177], v[214:217], v[30:33]
	v_mfma_f32_16x16x32_bf16 v[22:25], v[156:159], v[222:225], v[22:25]
	v_mfma_f32_16x16x32_bf16 v[14:17], v[174:177], v[222:225], v[14:17]
	s_setprio 0
	s_setprio 1
	v_mfma_f32_16x16x32_bf16 v[50:53], v[178:181], v[194:197], v[50:53]
	v_mfma_f32_16x16x32_bf16 v[42:45], v[186:189], v[194:197], v[42:45]
	v_mfma_f32_16x16x32_bf16 v[34:37], v[178:181], v[202:205], v[34:37]
	v_mfma_f32_16x16x32_bf16 v[26:29], v[186:189], v[202:205], v[26:29]
	v_mfma_f32_16x16x32_bf16 v[18:21], v[178:181], v[210:213], v[18:21]
	v_mfma_f32_16x16x32_bf16 v[10:13], v[186:189], v[210:213], v[10:13]
	v_mfma_f32_16x16x32_bf16 v[6:9], v[178:181], v[218:221], v[6:9]
	v_mfma_f32_16x16x32_bf16 v[2:5], v[186:189], v[218:221], v[2:5]
	v_mfma_f32_16x16x32_bf16 v[50:53], v[182:185], v[198:201], v[50:53]
	v_mfma_f32_16x16x32_bf16 v[42:45], v[190:193], v[198:201], v[42:45]
	v_mfma_f32_16x16x32_bf16 v[34:37], v[182:185], v[206:209], v[34:37]
	v_mfma_f32_16x16x32_bf16 v[26:29], v[190:193], v[206:209], v[26:29]
	v_mfma_f32_16x16x32_bf16 v[18:21], v[182:185], v[214:217], v[18:21]
	v_mfma_f32_16x16x32_bf16 v[10:13], v[190:193], v[214:217], v[10:13]
	v_mfma_f32_16x16x32_bf16 v[6:9], v[182:185], v[222:225], v[6:9]
	s_barrier
	v_mfma_f32_16x16x32_bf16 v[2:5], v[190:193], v[222:225], v[2:5]
	s_setprio 0
	s_add_i32 s64, 0, 0x18000
	v_add_u32_e32 v173, s64, v149
	s_add_i32 s65, 0, 0x1c000
	ds_read_b128 v[152:155], v173
	ds_read_b128 v[156:159], v173 offset:1024
	ds_read_b128 v[160:163], v173 offset:2048
	ds_read_b128 v[174:177], v173 offset:3072
	v_add_u32_e32 v173, s65, v149
	ds_read_b128 v[178:181], v173
	ds_read_b128 v[182:185], v173 offset:1024
	ds_read_b128 v[186:189], v173 offset:2048
	ds_read_b128 v[190:193], v173 offset:3072
	s_add_u32 s48, s48, 0x40000
	s_addc_u32 s49, s49, 0
	s_mov_b32 m0, s54
	ds_read_b128 v[194:197], v151 offset:32768
	ds_read_b128 v[198:201], v151 offset:33792
	ds_read_b128 v[202:205], v151 offset:34816
	ds_read_b128 v[206:209], v151 offset:35840
	ds_read_b128 v[210:213], v151 offset:36864
	ds_read_b128 v[214:217], v151 offset:37888
	ds_read_b128 v[218:221], v151 offset:38912
	ds_read_b128 v[222:225], v151 offset:39936
	global_load_lds_dwordx4 v140, s[48:49]
	s_mov_b32 m0, s55
	s_nop 0
	global_load_lds_dwordx4 v138, s[48:49]
	s_waitcnt vmcnt(8)
	s_waitcnt lgkmcnt(0)
	s_barrier
	s_setprio 1
	s_waitcnt lgkmcnt(0)
	v_mfma_f32_16x16x32_bf16 v[126:129], v[152:155], v[194:197], v[126:129]
	v_mfma_f32_16x16x32_bf16 v[122:125], v[160:163], v[194:197], v[122:125]
	v_mfma_f32_16x16x32_bf16 v[118:121], v[152:155], v[202:205], v[118:121]
	v_mfma_f32_16x16x32_bf16 v[110:113], v[160:163], v[202:205], v[110:113]
	v_mfma_f32_16x16x32_bf16 v[102:105], v[152:155], v[210:213], v[102:105]
	v_mfma_f32_16x16x32_bf16 v[94:97], v[160:163], v[210:213], v[94:97]
	v_mfma_f32_16x16x32_bf16 v[86:89], v[152:155], v[218:221], v[86:89]
	v_mfma_f32_16x16x32_bf16 v[78:81], v[160:163], v[218:221], v[78:81]
	v_mfma_f32_16x16x32_bf16 v[126:129], v[156:159], v[198:201], v[126:129]
	v_mfma_f32_16x16x32_bf16 v[122:125], v[174:177], v[198:201], v[122:125]
	v_mfma_f32_16x16x32_bf16 v[118:121], v[156:159], v[206:209], v[118:121]
	v_mfma_f32_16x16x32_bf16 v[110:113], v[174:177], v[206:209], v[110:113]
	v_mfma_f32_16x16x32_bf16 v[102:105], v[156:159], v[214:217], v[102:105]
	v_mfma_f32_16x16x32_bf16 v[94:97], v[174:177], v[214:217], v[94:97]
	v_mfma_f32_16x16x32_bf16 v[86:89], v[156:159], v[222:225], v[86:89]
	v_mfma_f32_16x16x32_bf16 v[78:81], v[174:177], v[222:225], v[78:81]
	s_setprio 0
	s_setprio 1
	v_mfma_f32_16x16x32_bf16 v[114:117], v[178:181], v[194:197], v[114:117]
	v_mfma_f32_16x16x32_bf16 v[106:109], v[186:189], v[194:197], v[106:109]
	v_mfma_f32_16x16x32_bf16 v[98:101], v[178:181], v[202:205], v[98:101]
	v_mfma_f32_16x16x32_bf16 v[90:93], v[186:189], v[202:205], v[90:93]
	v_mfma_f32_16x16x32_bf16 v[82:85], v[178:181], v[210:213], v[82:85]
	v_mfma_f32_16x16x32_bf16 v[74:77], v[186:189], v[210:213], v[74:77]
	v_mfma_f32_16x16x32_bf16 v[70:73], v[178:181], v[218:221], v[70:73]
	v_mfma_f32_16x16x32_bf16 v[66:69], v[186:189], v[218:221], v[66:69]
	v_mfma_f32_16x16x32_bf16 v[114:117], v[182:185], v[198:201], v[114:117]
	v_mfma_f32_16x16x32_bf16 v[106:109], v[190:193], v[198:201], v[106:109]
	v_mfma_f32_16x16x32_bf16 v[98:101], v[182:185], v[206:209], v[98:101]
	v_mfma_f32_16x16x32_bf16 v[90:93], v[190:193], v[206:209], v[90:93]
	v_mfma_f32_16x16x32_bf16 v[82:85], v[182:185], v[214:217], v[82:85]
	v_mfma_f32_16x16x32_bf16 v[74:77], v[190:193], v[214:217], v[74:77]
	v_mfma_f32_16x16x32_bf16 v[70:73], v[182:185], v[222:225], v[70:73]
	s_barrier
; #define PG8_STAGE(bufoff, gbase, voff) do { _Pragma("unroll") for (int _i = 0; _i < 2; ++_i) \
;         __builtin_amdgcn_global_load_lds((const unsigned*)((const char*)(gbase) + (voff)[_i]), (PG8_LAS unsigned*)(lds + (bufoff) + ldsw + _i * 8192), 16, 0, 0); } while (0)
; #define PG8_LDA(dst, b, h) do { _Pragma("unroll") for (int m = 0; m < 4; ++m) _Pragma("unroll") for (int k = 0; k < 2; ++k) dst[m][k] = *(const PG8_LAS bf16x8*)(lds + PG8_SA(b, h) + aoff + m * 2048 + k * 1024); } while (0)
; #define PG8_MMA(ai, bj, At, Bt) do { __builtin_amdgcn_s_setprio(1); _Pragma("unroll") for (int m = 0; m < 4; ++m) _Pragma("unroll") for (int n = 0; n < 2; ++n) _Pragma("unroll") for (int k = 0; k < 2; ++k) \
;         acc[ai][bj][m][n] = __builtin_amdgcn_mfma_f32_16x16x32_bf16(Bt[n][k], At[m][k], acc[ai][bj][m][n], 0, 0, 0); __builtin_amdgcn_s_setprio(0); } while (0)
; #define PG8_WAIT_V(n) asm volatile("s_waitcnt vmcnt(" #n ")" ::: "memory")
; #define PG8_WAIT_L(n) asm volatile("s_waitcnt lgkmcnt(" #n ")" ::: "memory")
; #define PG8_BAR __builtin_amdgcn_s_barrier()
; #define PG8_SCHED __builtin_amdgcn_sched_barrier(0)
; template <class Epi, class Sched, bool ALIGN_EPI = false, bool SP2 = false>
; __device__ __forceinline__ void gemm_phase(PG8_LAS unsigned char* lds, const Gemm g, const Sched& S, const Epi& E) {
;     ...
;             PG8_WAIT_V(8); PG8_WAIT_L(0); PG8_BAR; PG8_MMA(0, 0, At, B0); PG8_MMA(0, 1, At, B1); PG8_BAR; PG8_SCHED;
;             PG8_LDA(At, 1, 1); PG8_STAGE(PG8_SB(1, 0), b3, voffB); PG8_STAGE(PG8_SB(1, 1), b3 + hstep, voffB); PG8_STAGE(PG8_SA(1, 0), a3, voffA);
;             PG8_WAIT_V(8); PG8_WAIT_L(0); PG8_BAR; PG8_MMA(1, 0, At, B0); PG8_MMA(1, 1, At, B1); PG8_BAR; PG8_SCHED;
	v_mfma_f32_16x16x32_bf16 v[66:69], v[190:193], v[222:225], v[66:69]
	s_setprio 0
	s_add_i32 s48, s64, s34
	s_mov_b32 m0, s48
	ds_read_b128 v[194:197], v151 offset:49152
	ds_read_b128 v[198:201], v151 offset:50176
	ds_read_b128 v[202:205], v151 offset:51200
	ds_read_b128 v[206:209], v151 offset:52224
	ds_read_b128 v[210:213], v151 offset:53248
	ds_read_b128 v[214:217], v151 offset:54272
	ds_read_b128 v[218:221], v151 offset:55296
	ds_read_b128 v[222:225], v151 offset:56320
	global_load_lds_dwordx4 v130, s[98:99]
	s_add_i32 m0, s48, 0x2000
	s_add_u32 s46, s46, 0x40080
	s_addc_u32 s47, s47, 0
	s_add_i32 s48, s65, s34
	global_load_lds_dwordx4 v136, s[98:99]
	s_mov_b32 m0, s48
	s_nop 0
	global_load_lds_dwordx4 v130, s[46:47]
	s_add_i32 m0, s48, 0x2000
	s_nop 0
	global_load_lds_dwordx4 v136, s[46:47]
	s_mov_b32 m0, s56
	s_nop 0
	global_load_lds_dwordx4 v140, s[100:101]
	s_mov_b32 m0, s57
	s_nop 0
	global_load_lds_dwordx4 v138, s[100:101]
	s_waitcnt vmcnt(8)
	s_waitcnt lgkmcnt(0)
	s_barrier
	s_setprio 1
	s_waitcnt lgkmcnt(0)
	v_mfma_f32_16x16x32_bf16 v[62:65], v[152:155], v[194:197], v[62:65]
	v_mfma_f32_16x16x32_bf16 v[58:61], v[160:163], v[194:197], v[58:61]
	v_mfma_f32_16x16x32_bf16 v[54:57], v[152:155], v[202:205], v[54:57]
	v_mfma_f32_16x16x32_bf16 v[46:49], v[160:163], v[202:205], v[46:49]
	v_mfma_f32_16x16x32_bf16 v[38:41], v[152:155], v[210:213], v[38:41]
	v_mfma_f32_16x16x32_bf16 v[30:33], v[160:163], v[210:213], v[30:33]
	v_mfma_f32_16x16x32_bf16 v[22:25], v[152:155], v[218:221], v[22:25]
	v_mfma_f32_16x16x32_bf16 v[14:17], v[160:163], v[218:221], v[14:17]
	v_mfma_f32_16x16x32_bf16 v[62:65], v[156:159], v[198:201], v[62:65]
	v_mfma_f32_16x16x32_bf16 v[58:61], v[174:177], v[198:201], v[58:61]
	v_mfma_f32_16x16x32_bf16 v[54:57], v[156:159], v[206:209], v[54:57]
	v_mfma_f32_16x16x32_bf16 v[46:49], v[174:177], v[206:209], v[46:49]
	v_mfma_f32_16x16x32_bf16 v[38:41], v[156:159], v[214:217], v[38:41]
	v_mfma_f32_16x16x32_bf16 v[30:33], v[174:177], v[214:217], v[30:33]
	v_mfma_f32_16x16x32_bf16 v[22:25], v[156:159], v[222:225], v[22:25]
	v_mfma_f32_16x16x32_bf16 v[14:17], v[174:177], v[222:225], v[14:17]
	s_setprio 0
	s_setprio 1
	v_mfma_f32_16x16x32_bf16 v[50:53], v[178:181], v[194:197], v[50:53]
	v_mfma_f32_16x16x32_bf16 v[42:45], v[186:189], v[194:197], v[42:45]
	v_mfma_f32_16x16x32_bf16 v[34:37], v[178:181], v[202:205], v[34:37]
	v_mfma_f32_16x16x32_bf16 v[26:29], v[186:189], v[202:205], v[26:29]
	v_mfma_f32_16x16x32_bf16 v[18:21], v[178:181], v[210:213], v[18:21]
	v_mfma_f32_16x16x32_bf16 v[10:13], v[186:189], v[210:213], v[10:13]
	v_mfma_f32_16x16x32_bf16 v[6:9], v[178:181], v[218:221], v[6:9]
	v_mfma_f32_16x16x32_bf16 v[2:5], v[186:189], v[218:221], v[2:5]
	v_mfma_f32_16x16x32_bf16 v[50:53], v[182:185], v[198:201], v[50:53]
	v_mfma_f32_16x16x32_bf16 v[42:45], v[190:193], v[198:201], v[42:45]
	v_mfma_f32_16x16x32_bf16 v[34:37], v[182:185], v[206:209], v[34:37]
	v_mfma_f32_16x16x32_bf16 v[26:29], v[190:193], v[206:209], v[26:29]
	v_mfma_f32_16x16x32_bf16 v[18:21], v[182:185], v[214:217], v[18:21]
	v_mfma_f32_16x16x32_bf16 v[10:13], v[190:193], v[214:217], v[10:13]
	v_mfma_f32_16x16x32_bf16 v[6:9], v[182:185], v[222:225], v[6:9]
	s_barrier
	v_mfma_f32_16x16x32_bf16 v[2:5], v[190:193], v[222:225], v[2:5]
	s_setprio 0
	s_add_i32 s63, s63, 2
	s_add_u32 s44, s44, 0x100
	s_addc_u32 s45, s45, 0
	s_add_u32 s61, s61, 0x100
	s_addc_u32 s62, s62, 0
	s_cmp_gt_u32 s63, 13
	s_cbranch_scc0 .LBB0_121
	s_nop 0
	s_and_b64 vcc, exec, s[6:7]
	s_cbranch_vccz .LBB0_124
	s_barrier

; #define PG8_STAGE(bufoff, gbase, voff) do { _Pragma("unroll") for (int _i = 0; _i < 2; ++_i) \
;         __builtin_amdgcn_global_load_lds((const unsigned*)((const char*)(gbase) + (voff)[_i]), (PG8_LAS unsigned*)(lds + (bufoff) + ldsw + _i * 8192), 16, 0, 0); } while (0)
; #define PG8_LDA(dst, b, h) do { _Pragma("unroll") for (int m = 0; m < 4; ++m) _Pragma("unroll") for (int k = 0; k < 2; ++k) dst[m][k] = *(const PG8_LAS bf16x8*)(lds + PG8_SA(b, h) + aoff + m * 2048 + k * 1024); } while (0)
; #define PG8_LDB(dst, b, h) do { _Pragma("unroll") for (int n = 0; n < 2; ++n) _Pragma("unroll") for (int k = 0; k < 2; ++k) dst[n][k] = *(const PG8_LAS bf16x8*)(lds + PG8_SB(b, h) + boff + n * 2048 + k * 1024); } while (0)
; #define PG8_MMA(ai, bj, At, Bt) do { __builtin_amdgcn_s_setprio(1); _Pragma("unroll") for (int m = 0; m < 4; ++m) _Pragma("unroll") for (int n = 0; n < 2; ++n) _Pragma("unroll") for (int k = 0; k < 2; ++k) \
;         acc[ai][bj][m][n] = __builtin_amdgcn_mfma_f32_16x16x32_bf16(Bt[n][k], At[m][k], acc[ai][bj][m][n], 0, 0, 0); __builtin_amdgcn_s_setprio(0); } while (0)
; #define PG8_WAIT_V(n) asm volatile("s_waitcnt vmcnt(" #n ")" ::: "memory")
; #define PG8_WAIT_L(n) asm volatile("s_waitcnt lgkmcnt(" #n ")" ::: "memory")
; template <class Epi, class Sched, bool ALIGN_EPI = false, bool SP2 = false>
; __device__ __forceinline__ void gemm_phase(PG8_LAS unsigned char* lds, const Gemm g, const Sched& S, const Epi& E) {
;     ...
;             const bool last = (t == nt - 2);
;             const char* a1 = cA + (size_t)(t + 1) * kstep;
;             const char* a2 = last ? nA : cA + (size_t)(t + 2) * kstep; const char* b2 = last ? nB : cB + (size_t)(t + 2) * kstep;
;             const char* a3 = a2 + kstep; const char* b3 = b2 + kstep;
;             if (last && has_next) S.a_ready(nxt);
;             if constexpr (SP2) {
;             PG8_LDB(B0, 0, 0); PG8_LDB(B1, 0, 1); PG8_SCHED; PG8_LDA(At, 0, 0); PG8_STAGE(PG8_SA(1, 1), a1 + hstep, voffA);
;             PG8_WAIT_V(8); PG8_WAIT_L(0); PG8_BAR; PG8_MMA(0, 0, At, B0); PG8_MMA(0, 1, At, B1); PG8_BAR; PG8_SCHED;
;             PG8_LDA(At, 0, 1); PG8_STAGE(PG8_SB(0, 0), b2, voffB); PG8_STAGE(PG8_SB(0, 1), b2 + hstep, voffB); PG8_STAGE(PG8_SA(0, 0), a2, voffA);
;             PG8_WAIT_V(8); PG8_WAIT_L(0); PG8_BAR; PG8_MMA(1, 0, At, B0); PG8_MMA(1, 1, At, B1); PG8_BAR; PG8_SCHED;
.LBB0_811:
	ds_read_b128 v[130:133], v159
	ds_read_b128 v[152:155], v159 offset:1024
	ds_read_b128 v[166:169], v159 offset:2048
	ds_read_b128 v[170:173], v159 offset:3072
	ds_read_b128 v[174:177], v160
	ds_read_b128 v[178:181], v160 offset:1024
	ds_read_b128 v[182:185], v160 offset:2048
	ds_read_b128 v[186:189], v160 offset:3072
	s_add_u32 s42, s4, 0xfffc0080
	s_addc_u32 s43, s5, -1
	s_cmp_eq_u32 s47, 12
	s_cselect_b32 s45, s35, s43
	s_cselect_b32 s44, s34, s42
	s_cselect_b32 s43, s6, s46
	s_cselect_b32 s42, s23, s25
	s_add_i32 m0, s39, 0xc000
	ds_read_b128 v[190:193], v161
	ds_read_b128 v[194:197], v161 offset:1024
	ds_read_b128 v[198:201], v161 offset:2048
	ds_read_b128 v[202:205], v161 offset:3072
	ds_read_b128 v[206:209], v161 offset:4096
	ds_read_b128 v[210:213], v161 offset:5120
	ds_read_b128 v[214:217], v161 offset:6144
	ds_read_b128 v[218:221], v161 offset:7168
	global_load_lds_dwordx4 v144, s[4:5]
	s_add_i32 m0, s39, 0xe000
	s_nop 0
	global_load_lds_dwordx4 v146, s[4:5]
	s_waitcnt vmcnt(8)
	s_waitcnt lgkmcnt(0)
	s_barrier
	s_setprio 1
	s_waitcnt lgkmcnt(0)
	v_mfma_f32_16x16x32_bf16 v[126:129], v[130:133], v[190:193], v[126:129]
	v_mfma_f32_16x16x32_bf16 v[122:125], v[166:169], v[190:193], v[122:125]
	v_mfma_f32_16x16x32_bf16 v[110:113], v[130:133], v[198:201], v[110:113]
	v_mfma_f32_16x16x32_bf16 v[106:109], v[166:169], v[198:201], v[106:109]
	v_mfma_f32_16x16x32_bf16 v[94:97], v[130:133], v[206:209], v[94:97]
	v_mfma_f32_16x16x32_bf16 v[90:93], v[166:169], v[206:209], v[90:93]
	v_mfma_f32_16x16x32_bf16 v[78:81], v[130:133], v[214:217], v[78:81]
	v_mfma_f32_16x16x32_bf16 v[74:77], v[166:169], v[214:217], v[74:77]
	v_mfma_f32_16x16x32_bf16 v[126:129], v[152:155], v[194:197], v[126:129]
	v_mfma_f32_16x16x32_bf16 v[122:125], v[170:173], v[194:197], v[122:125]
	v_mfma_f32_16x16x32_bf16 v[110:113], v[152:155], v[202:205], v[110:113]
	v_mfma_f32_16x16x32_bf16 v[106:109], v[170:173], v[202:205], v[106:109]
	v_mfma_f32_16x16x32_bf16 v[94:97], v[152:155], v[210:213], v[94:97]
	v_mfma_f32_16x16x32_bf16 v[90:93], v[170:173], v[210:213], v[90:93]
	v_mfma_f32_16x16x32_bf16 v[78:81], v[152:155], v[218:221], v[78:81]
	v_mfma_f32_16x16x32_bf16 v[74:77], v[170:173], v[218:221], v[74:77]
	s_setprio 0
	s_setprio 1
	v_mfma_f32_16x16x32_bf16 v[118:121], v[174:177], v[190:193], v[118:121]
	v_mfma_f32_16x16x32_bf16 v[114:117], v[182:185], v[190:193], v[114:117]
	v_mfma_f32_16x16x32_bf16 v[102:105], v[174:177], v[198:201], v[102:105]
	v_mfma_f32_16x16x32_bf16 v[98:101], v[182:185], v[198:201], v[98:101]
	v_mfma_f32_16x16x32_bf16 v[86:89], v[174:177], v[206:209], v[86:89]
	v_mfma_f32_16x16x32_bf16 v[82:85], v[182:185], v[206:209], v[82:85]
	v_mfma_f32_16x16x32_bf16 v[70:73], v[174:177], v[214:217], v[70:73]
	v_mfma_f32_16x16x32_bf16 v[66:69], v[182:185], v[214:217], v[66:69]
	v_mfma_f32_16x16x32_bf16 v[118:121], v[178:181], v[194:197], v[118:121]
	v_mfma_f32_16x16x32_bf16 v[114:117], v[186:189], v[194:197], v[114:117]
	v_mfma_f32_16x16x32_bf16 v[102:105], v[178:181], v[202:205], v[102:105]
	v_mfma_f32_16x16x32_bf16 v[98:101], v[186:189], v[202:205], v[98:101]
	v_mfma_f32_16x16x32_bf16 v[86:89], v[178:181], v[210:213], v[86:89]
	v_mfma_f32_16x16x32_bf16 v[82:85], v[186:189], v[210:213], v[82:85]
	v_mfma_f32_16x16x32_bf16 v[70:73], v[178:181], v[218:221], v[70:73]
	s_barrier
	v_mfma_f32_16x16x32_bf16 v[66:69], v[186:189], v[218:221], v[66:69]
	s_setprio 0
	s_add_i32 s61, s54, s33
	s_add_u32 s98, s42, s12
	s_addc_u32 s99, s43, s13
	s_mov_b32 m0, s61
	ds_read_b128 v[190:193], v161 offset:16384
	ds_read_b128 v[194:197], v161 offset:17408
	ds_read_b128 v[198:201], v161 offset:18432
	ds_read_b128 v[202:205], v161 offset:19456
	ds_read_b128 v[206:209], v161 offset:20480
	ds_read_b128 v[210:213], v161 offset:21504
	ds_read_b128 v[214:217], v161 offset:22528
	ds_read_b128 v[218:221], v161 offset:23552
	global_load_lds_dwordx4 v136, s[42:43]
	s_add_i32 m0, s61, 0x2000
	s_add_u32 s62, s42, 0x40000
	s_addc_u32 s63, s43, 0
	s_add_i32 s61, s55, s33
	global_load_lds_dwordx4 v140, s[42:43]
	s_mov_b32 m0, s61
	s_nop 0
	global_load_lds_dwordx4 v136, s[62:63]
	s_add_i32 m0, s61, 0x2000
	s_nop 0
	global_load_lds_dwordx4 v140, s[62:63]
	s_add_u32 s100, s44, s12
	s_addc_u32 s101, s45, s13
	s_mov_b32 m0, s39
	s_nop 0
	global_load_lds_dwordx4 v134, s[44:45]
	s_mov_b32 m0, s49
	s_nop 0
	global_load_lds_dwordx4 v138, s[44:45]
	s_waitcnt vmcnt(8)
	s_waitcnt lgkmcnt(0)
	s_barrier
	s_setprio 1
	s_waitcnt lgkmcnt(0)
	v_mfma_f32_16x16x32_bf16 v[62:65], v[130:133], v[190:193], v[62:65]
	v_mfma_f32_16x16x32_bf16 v[58:61], v[166:169], v[190:193], v[58:61]
	v_mfma_f32_16x16x32_bf16 v[46:49], v[130:133], v[198:201], v[46:49]
	v_mfma_f32_16x16x32_bf16 v[42:45], v[166:169], v[198:201], v[42:45]
	v_mfma_f32_16x16x32_bf16 v[30:33], v[130:133], v[206:209], v[30:33]
	v_mfma_f32_16x16x32_bf16 v[26:29], v[166:169], v[206:209], v[26:29]
	v_mfma_f32_16x16x32_bf16 v[14:17], v[130:133], v[214:217], v[14:17]
	v_mfma_f32_16x16x32_bf16 v[10:13], v[166:169], v[214:217], v[10:13]
	v_mfma_f32_16x16x32_bf16 v[62:65], v[152:155], v[194:197], v[62:65]
	v_mfma_f32_16x16x32_bf16 v[58:61], v[170:173], v[194:197], v[58:61]
	v_mfma_f32_16x16x32_bf16 v[46:49], v[152:155], v[202:205], v[46:49]
	v_mfma_f32_16x16x32_bf16 v[42:45], v[170:173], v[202:205], v[42:45]
	v_mfma_f32_16x16x32_bf16 v[30:33], v[152:155], v[210:213], v[30:33]
	v_mfma_f32_16x16x32_bf16 v[26:29], v[170:173], v[210:213], v[26:29]
	v_mfma_f32_16x16x32_bf16 v[14:17], v[152:155], v[218:221], v[14:17]
	v_mfma_f32_16x16x32_bf16 v[10:13], v[170:173], v[218:221], v[10:13]
	s_setprio 0
	s_setprio 1
	v_mfma_f32_16x16x32_bf16 v[54:57], v[174:177], v[190:193], v[54:57]
	v_mfma_f32_16x16x32_bf16 v[50:53], v[182:185], v[190:193], v[50:53]
	v_mfma_f32_16x16x32_bf16 v[38:41], v[174:177], v[198:201], v[38:41]
	v_mfma_f32_16x16x32_bf16 v[34:37], v[182:185], v[198:201], v[34:37]
	v_mfma_f32_16x16x32_bf16 v[22:25], v[174:177], v[206:209], v[22:25]
	v_mfma_f32_16x16x32_bf16 v[18:21], v[182:185], v[206:209], v[18:21]
	v_mfma_f32_16x16x32_bf16 v[6:9], v[174:177], v[214:217], v[6:9]
	v_mfma_f32_16x16x32_bf16 v[2:5], v[182:185], v[214:217], v[2:5]
	v_mfma_f32_16x16x32_bf16 v[54:57], v[178:181], v[194:197], v[54:57]
	v_mfma_f32_16x16x32_bf16 v[50:53], v[186:189], v[194:197], v[50:53]
	v_mfma_f32_16x16x32_bf16 v[38:41], v[178:181], v[202:205], v[38:41]
	v_mfma_f32_16x16x32_bf16 v[34:37], v[186:189], v[202:205], v[34:37]
	v_mfma_f32_16x16x32_bf16 v[22:25], v[178:181], v[210:213], v[22:25]
	v_mfma_f32_16x16x32_bf16 v[18:21], v[186:189], v[210:213], v[18:21]
	v_mfma_f32_16x16x32_bf16 v[6:9], v[178:181], v[218:221], v[6:9]
	s_barrier
; #define PG8_STAGE(bufoff, gbase, voff) do { _Pragma("unroll") for (int _i = 0; _i < 2; ++_i) \
;         __builtin_amdgcn_global_load_lds((const unsigned*)((const char*)(gbase) + (voff)[_i]), (PG8_LAS unsigned*)(lds + (bufoff) + ldsw + _i * 8192), 16, 0, 0); } while (0)
; #define PG8_LDA(dst, b, h) do { _Pragma("unroll") for (int m = 0; m < 4; ++m) _Pragma("unroll") for (int k = 0; k < 2; ++k) dst[m][k] = *(const PG8_LAS bf16x8*)(lds + PG8_SA(b, h) + aoff + m * 2048 + k * 1024); } while (0)
; #define PG8_LDB(dst, b, h) do { _Pragma("unroll") for (int n = 0; n < 2; ++n) _Pragma("unroll") for (int k = 0; k < 2; ++k) dst[n][k] = *(const PG8_LAS bf16x8*)(lds + PG8_SB(b, h) + boff + n * 2048 + k * 1024); } while (0)
; #define PG8_MMA(ai, bj, At, Bt) do { __builtin_amdgcn_s_setprio(1); _Pragma("unroll") for (int m = 0; m < 4; ++m) _Pragma("unroll") for (int n = 0; n < 2; ++n) _Pragma("unroll") for (int k = 0; k < 2; ++k) \
;         acc[ai][bj][m][n] = __builtin_amdgcn_mfma_f32_16x16x32_bf16(Bt[n][k], At[m][k], acc[ai][bj][m][n], 0, 0, 0); __builtin_amdgcn_s_setprio(0); } while (0)
; #define PG8_WAIT_V(n) asm volatile("s_waitcnt vmcnt(" #n ")" ::: "memory")
; #define PG8_WAIT_L(n) asm volatile("s_waitcnt lgkmcnt(" #n ")" ::: "memory")
; #define PG8_BAR __builtin_amdgcn_s_barrier()
; #define PG8_SCHED __builtin_amdgcn_sched_barrier(0)
; template <class Epi, class Sched, bool ALIGN_EPI = false, bool SP2 = false>
; __device__ __forceinline__ void gemm_phase(PG8_LAS unsigned char* lds, const Gemm g, const Sched& S, const Epi& E) {
;     ...
;             PG8_WAIT_V(8); PG8_WAIT_L(0); PG8_BAR; PG8_MMA(1, 0, At, B0); PG8_MMA(1, 1, At, B1); PG8_BAR; PG8_SCHED;
;             PG8_LDB(B0, 1, 0); PG8_LDB(B1, 1, 1); PG8_SCHED; PG8_LDA(At, 1, 0); PG8_STAGE(PG8_SA(0, 1), a2 + hstep, voffA);
;             PG8_WAIT_V(8); PG8_WAIT_L(0); PG8_BAR; PG8_MMA(0, 0, At, B0); PG8_MMA(0, 1, At, B1); PG8_BAR; PG8_SCHED;
;             PG8_LDA(At, 1, 1); PG8_STAGE(PG8_SB(1, 0), b3, voffB); PG8_STAGE(PG8_SB(1, 1), b3 + hstep, voffB); PG8_STAGE(PG8_SA(1, 0), a3, voffA);
;             PG8_WAIT_V(8); PG8_WAIT_L(0); PG8_BAR; PG8_MMA(1, 0, At, B0); PG8_MMA(1, 1, At, B1); PG8_BAR; PG8_SCHED;
	v_mfma_f32_16x16x32_bf16 v[2:5], v[186:189], v[218:221], v[2:5]
	s_setprio 0
	s_add_i32 s61, 0, 0x18000
	v_add_u32_e32 v142, s61, v157
	s_add_i32 s62, 0, 0x1c000
	ds_read_b128 v[130:133], v142
	ds_read_b128 v[152:155], v142 offset:1024
	ds_read_b128 v[166:169], v142 offset:2048
	ds_read_b128 v[170:173], v142 offset:3072
	v_add_u32_e32 v142, s62, v157
	ds_read_b128 v[174:177], v142
	ds_read_b128 v[178:181], v142 offset:1024
	ds_read_b128 v[182:185], v142 offset:2048
	ds_read_b128 v[186:189], v142 offset:3072
	s_add_u32 s44, s44, 0x40000
	s_addc_u32 s45, s45, 0
	s_mov_b32 m0, s50
	ds_read_b128 v[190:193], v161 offset:32768
	ds_read_b128 v[194:197], v161 offset:33792
	ds_read_b128 v[198:201], v161 offset:34816
	ds_read_b128 v[202:205], v161 offset:35840
	ds_read_b128 v[206:209], v161 offset:36864
	ds_read_b128 v[210:213], v161 offset:37888
	ds_read_b128 v[214:217], v161 offset:38912
	ds_read_b128 v[218:221], v161 offset:39936
	global_load_lds_dwordx4 v134, s[44:45]
	s_mov_b32 m0, s51
	s_nop 0
	global_load_lds_dwordx4 v138, s[44:45]
	s_waitcnt vmcnt(8)
	s_waitcnt lgkmcnt(0)
	s_barrier
	s_setprio 1
	s_waitcnt lgkmcnt(0)
	v_mfma_f32_16x16x32_bf16 v[126:129], v[130:133], v[190:193], v[126:129]
	v_mfma_f32_16x16x32_bf16 v[122:125], v[166:169], v[190:193], v[122:125]
	v_mfma_f32_16x16x32_bf16 v[110:113], v[130:133], v[198:201], v[110:113]
	v_mfma_f32_16x16x32_bf16 v[106:109], v[166:169], v[198:201], v[106:109]
	v_mfma_f32_16x16x32_bf16 v[94:97], v[130:133], v[206:209], v[94:97]
	v_mfma_f32_16x16x32_bf16 v[90:93], v[166:169], v[206:209], v[90:93]
	v_mfma_f32_16x16x32_bf16 v[78:81], v[130:133], v[214:217], v[78:81]
	v_mfma_f32_16x16x32_bf16 v[74:77], v[166:169], v[214:217], v[74:77]
	v_mfma_f32_16x16x32_bf16 v[126:129], v[152:155], v[194:197], v[126:129]
	v_mfma_f32_16x16x32_bf16 v[122:125], v[170:173], v[194:197], v[122:125]
	v_mfma_f32_16x16x32_bf16 v[110:113], v[152:155], v[202:205], v[110:113]
	v_mfma_f32_16x16x32_bf16 v[106:109], v[170:173], v[202:205], v[106:109]
	v_mfma_f32_16x16x32_bf16 v[94:97], v[152:155], v[210:213], v[94:97]
	v_mfma_f32_16x16x32_bf16 v[90:93], v[170:173], v[210:213], v[90:93]
	v_mfma_f32_16x16x32_bf16 v[78:81], v[152:155], v[218:221], v[78:81]
	v_mfma_f32_16x16x32_bf16 v[74:77], v[170:173], v[218:221], v[74:77]
	s_setprio 0
	s_setprio 1
	v_mfma_f32_16x16x32_bf16 v[118:121], v[174:177], v[190:193], v[118:121]
	v_mfma_f32_16x16x32_bf16 v[114:117], v[182:185], v[190:193], v[114:117]
	v_mfma_f32_16x16x32_bf16 v[102:105], v[174:177], v[198:201], v[102:105]
	v_mfma_f32_16x16x32_bf16 v[98:101], v[182:185], v[198:201], v[98:101]
	v_mfma_f32_16x16x32_bf16 v[86:89], v[174:177], v[206:209], v[86:89]
	v_mfma_f32_16x16x32_bf16 v[82:85], v[182:185], v[206:209], v[82:85]
	v_mfma_f32_16x16x32_bf16 v[70:73], v[174:177], v[214:217], v[70:73]
	v_mfma_f32_16x16x32_bf16 v[66:69], v[182:185], v[214:217], v[66:69]
	v_mfma_f32_16x16x32_bf16 v[118:121], v[178:181], v[194:197], v[118:121]
	v_mfma_f32_16x16x32_bf16 v[114:117], v[186:189], v[194:197], v[114:117]
	v_mfma_f32_16x16x32_bf16 v[102:105], v[178:181], v[202:205], v[102:105]
	v_mfma_f32_16x16x32_bf16 v[98:101], v[186:189], v[202:205], v[98:101]
	v_mfma_f32_16x16x32_bf16 v[86:89], v[178:181], v[210:213], v[86:89]
	v_mfma_f32_16x16x32_bf16 v[82:85], v[186:189], v[210:213], v[82:85]
	v_mfma_f32_16x16x32_bf16 v[70:73], v[178:181], v[218:221], v[70:73]
	s_barrier
	v_mfma_f32_16x16x32_bf16 v[66:69], v[186:189], v[218:221], v[66:69]
	s_setprio 0
	s_add_i32 s44, s61, s33
	s_mov_b32 m0, s44
	ds_read_b128 v[190:193], v161 offset:49152
	ds_read_b128 v[194:197], v161 offset:50176
	ds_read_b128 v[198:201], v161 offset:51200
	ds_read_b128 v[202:205], v161 offset:52224
	ds_read_b128 v[206:209], v161 offset:53248
	ds_read_b128 v[210:213], v161 offset:54272
	ds_read_b128 v[214:217], v161 offset:55296
	ds_read_b128 v[218:221], v161 offset:56320
	global_load_lds_dwordx4 v136, s[98:99]
	s_add_i32 m0, s44, 0x2000
	s_add_u32 s42, s42, 0x40080
	s_addc_u32 s43, s43, 0
	s_add_i32 s44, s62, s33
	global_load_lds_dwordx4 v140, s[98:99]
	s_mov_b32 m0, s44
	s_nop 0
	global_load_lds_dwordx4 v136, s[42:43]
	s_add_i32 m0, s44, 0x2000
	s_nop 0
	global_load_lds_dwordx4 v140, s[42:43]
	s_mov_b32 m0, s52
	s_nop 0
	global_load_lds_dwordx4 v134, s[100:101]
	s_mov_b32 m0, s53
	s_nop 0
	global_load_lds_dwordx4 v138, s[100:101]
	s_waitcnt vmcnt(8)
	s_waitcnt lgkmcnt(0)
	s_barrier
	s_setprio 1
	s_waitcnt lgkmcnt(0)
	v_mfma_f32_16x16x32_bf16 v[62:65], v[130:133], v[190:193], v[62:65]
	v_mfma_f32_16x16x32_bf16 v[58:61], v[166:169], v[190:193], v[58:61]
	v_mfma_f32_16x16x32_bf16 v[46:49], v[130:133], v[198:201], v[46:49]
	v_mfma_f32_16x16x32_bf16 v[42:45], v[166:169], v[198:201], v[42:45]
	v_mfma_f32_16x16x32_bf16 v[30:33], v[130:133], v[206:209], v[30:33]
	v_mfma_f32_16x16x32_bf16 v[26:29], v[166:169], v[206:209], v[26:29]
	v_mfma_f32_16x16x32_bf16 v[14:17], v[130:133], v[214:217], v[14:17]
	v_mfma_f32_16x16x32_bf16 v[10:13], v[166:169], v[214:217], v[10:13]
	v_mfma_f32_16x16x32_bf16 v[62:65], v[152:155], v[194:197], v[62:65]
	v_mfma_f32_16x16x32_bf16 v[58:61], v[170:173], v[194:197], v[58:61]
	v_mfma_f32_16x16x32_bf16 v[46:49], v[152:155], v[202:205], v[46:49]
	v_mfma_f32_16x16x32_bf16 v[42:45], v[170:173], v[202:205], v[42:45]
	v_mfma_f32_16x16x32_bf16 v[30:33], v[152:155], v[210:213], v[30:33]
	v_mfma_f32_16x16x32_bf16 v[26:29], v[170:173], v[210:213], v[26:29]
	v_mfma_f32_16x16x32_bf16 v[14:17], v[152:155], v[218:221], v[14:17]
	v_mfma_f32_16x16x32_bf16 v[10:13], v[170:173], v[218:221], v[10:13]
	s_setprio 0
	s_setprio 1
	v_mfma_f32_16x16x32_bf16 v[54:57], v[174:177], v[190:193], v[54:57]
	v_mfma_f32_16x16x32_bf16 v[50:53], v[182:185], v[190:193], v[50:53]
	v_mfma_f32_16x16x32_bf16 v[38:41], v[174:177], v[198:201], v[38:41]
	v_mfma_f32_16x16x32_bf16 v[34:37], v[182:185], v[198:201], v[34:37]
	v_mfma_f32_16x16x32_bf16 v[22:25], v[174:177], v[206:209], v[22:25]
	v_mfma_f32_16x16x32_bf16 v[18:21], v[182:185], v[206:209], v[18:21]
	v_mfma_f32_16x16x32_bf16 v[6:9], v[174:177], v[214:217], v[6:9]
	v_mfma_f32_16x16x32_bf16 v[2:5], v[182:185], v[214:217], v[2:5]
	v_mfma_f32_16x16x32_bf16 v[54:57], v[178:181], v[194:197], v[54:57]
	v_mfma_f32_16x16x32_bf16 v[50:53], v[186:189], v[194:197], v[50:53]
	v_mfma_f32_16x16x32_bf16 v[38:41], v[178:181], v[202:205], v[38:41]
	v_mfma_f32_16x16x32_bf16 v[34:37], v[186:189], v[202:205], v[34:37]
	v_mfma_f32_16x16x32_bf16 v[22:25], v[178:181], v[210:213], v[22:25]
	v_mfma_f32_16x16x32_bf16 v[18:21], v[186:189], v[210:213], v[18:21]
	v_mfma_f32_16x16x32_bf16 v[6:9], v[178:181], v[218:221], v[6:9]
	s_barrier
	v_mfma_f32_16x16x32_bf16 v[2:5], v[186:189], v[218:221], v[2:5]
	s_setprio 0
	s_add_i32 s47, s47, 2
	s_add_u32 s4, s4, 0x100
	s_addc_u32 s5, s5, 0
	s_add_u32 s25, s25, 0x100
	s_addc_u32 s46, s46, 0
	s_cmp_gt_u32 s47, 13
	s_cbranch_scc0 .LBB0_811
	s_nop 0
	s_and_b64 vcc, exec, s[14:15]
	s_cbranch_vccz .LBB0_814
	s_barrier

; #define PG8_STAGE(bufoff, gbase, voff) do { _Pragma("unroll") for (int _i = 0; _i < 2; ++_i) \
;         __builtin_amdgcn_global_load_lds((const unsigned*)((const char*)(gbase) + (voff)[_i]), (PG8_LAS unsigned*)(lds + (bufoff) + ldsw + _i * 8192), 16, 0, 0); } while (0)
; #define PG8_LDA(dst, b, h) do { _Pragma("unroll") for (int m = 0; m < 4; ++m) _Pragma("unroll") for (int k = 0; k < 2; ++k) dst[m][k] = *(const PG8_LAS bf16x8*)(lds + PG8_SA(b, h) + aoff + m * 2048 + k * 1024); } while (0)
; #define PG8_LDB(dst, b, h) do { _Pragma("unroll") for (int n = 0; n < 2; ++n) _Pragma("unroll") for (int k = 0; k < 2; ++k) dst[n][k] = *(const PG8_LAS bf16x8*)(lds + PG8_SB(b, h) + boff + n * 2048 + k * 1024); } while (0)
; #define PG8_MMA(ai, bj, At, Bt) do { __builtin_amdgcn_s_setprio(1); _Pragma("unroll") for (int m = 0; m < 4; ++m) _Pragma("unroll") for (int n = 0; n < 2; ++n) _Pragma("unroll") for (int k = 0; k < 2; ++k) \
;         acc[ai][bj][m][n] = __builtin_amdgcn_mfma_f32_16x16x32_bf16(Bt[n][k], At[m][k], acc[ai][bj][m][n], 0, 0, 0); __builtin_amdgcn_s_setprio(0); } while (0)
; #define PG8_WAIT_V(n) asm volatile("s_waitcnt vmcnt(" #n ")" ::: "memory")
; #define PG8_WAIT_L(n) asm volatile("s_waitcnt lgkmcnt(" #n ")" ::: "memory")
; template <class Epi, class Sched, bool ALIGN_EPI = false, bool SP2 = false>
; __device__ __forceinline__ void gemm_phase(PG8_LAS unsigned char* lds, const Gemm g, const Sched& S, const Epi& E) {
;     ...
;             const bool last = (t == nt - 2);
;             const char* a1 = cA + (size_t)(t + 1) * kstep;
;             const char* a2 = last ? nA : cA + (size_t)(t + 2) * kstep; const char* b2 = last ? nB : cB + (size_t)(t + 2) * kstep;
;             const char* a3 = a2 + kstep; const char* b3 = b2 + kstep;
;             if (last && has_next) S.a_ready(nxt);
;             if constexpr (SP2) {
;             PG8_LDB(B0, 0, 0); PG8_LDB(B1, 0, 1); PG8_SCHED; PG8_LDA(At, 0, 0); PG8_STAGE(PG8_SA(1, 1), a1 + hstep, voffA);
;             PG8_WAIT_V(8); PG8_WAIT_L(0); PG8_BAR; PG8_MMA(0, 0, At, B0); PG8_MMA(0, 1, At, B1); PG8_BAR; PG8_SCHED;
;             PG8_LDA(At, 0, 1); PG8_STAGE(PG8_SB(0, 0), b2, voffB); PG8_STAGE(PG8_SB(0, 1), b2 + hstep, voffB); PG8_STAGE(PG8_SA(0, 0), a2, voffA);
;             PG8_WAIT_V(8); PG8_WAIT_L(0); PG8_BAR; PG8_MMA(1, 0, At, B0); PG8_MMA(1, 1, At, B1); PG8_BAR; PG8_SCHED;
.LBB0_884:
	ds_read_b128 v[130:133], v159
	ds_read_b128 v[146:149], v159 offset:1024
	ds_read_b128 v[150:153], v159 offset:2048
	ds_read_b128 v[162:165], v159 offset:3072
	ds_read_b128 v[166:169], v160
	ds_read_b128 v[170:173], v160 offset:1024
	ds_read_b128 v[174:177], v160 offset:2048
	ds_read_b128 v[178:181], v160 offset:3072
	s_add_u32 s46, s44, 0xfffc0080
	s_addc_u32 s47, s45, -1
	s_cmp_eq_u32 s60, 12
	s_cselect_b32 s49, s35, s47
	s_cselect_b32 s48, s34, s46
	s_cselect_b32 s47, s17, s59
	s_cselect_b32 s46, s19, s58
	s_add_i32 m0, s50, 0xc000
	ds_read_b128 v[182:185], v161
	ds_read_b128 v[186:189], v161 offset:1024
	ds_read_b128 v[190:193], v161 offset:2048
	ds_read_b128 v[194:197], v161 offset:3072
	ds_read_b128 v[198:201], v161 offset:4096
	ds_read_b128 v[202:205], v161 offset:5120
	ds_read_b128 v[206:209], v161 offset:6144
	ds_read_b128 v[210:213], v161 offset:7168
	global_load_lds_dwordx4 v142, s[44:45]
	s_add_i32 m0, s50, 0xe000
	s_nop 0
	global_load_lds_dwordx4 v144, s[44:45]
	s_waitcnt vmcnt(8)
	s_waitcnt lgkmcnt(0)
	s_barrier
	s_setprio 1
	s_waitcnt lgkmcnt(0)
	v_mfma_f32_16x16x32_bf16 v[126:129], v[130:133], v[182:185], v[126:129]
	v_mfma_f32_16x16x32_bf16 v[122:125], v[150:153], v[182:185], v[122:125]
	v_mfma_f32_16x16x32_bf16 v[110:113], v[130:133], v[190:193], v[110:113]
	v_mfma_f32_16x16x32_bf16 v[106:109], v[150:153], v[190:193], v[106:109]
	v_mfma_f32_16x16x32_bf16 v[94:97], v[130:133], v[198:201], v[94:97]
	v_mfma_f32_16x16x32_bf16 v[90:93], v[150:153], v[198:201], v[90:93]
	v_mfma_f32_16x16x32_bf16 v[78:81], v[130:133], v[206:209], v[78:81]
	v_mfma_f32_16x16x32_bf16 v[74:77], v[150:153], v[206:209], v[74:77]
	v_mfma_f32_16x16x32_bf16 v[126:129], v[146:149], v[186:189], v[126:129]
	v_mfma_f32_16x16x32_bf16 v[122:125], v[162:165], v[186:189], v[122:125]
	v_mfma_f32_16x16x32_bf16 v[110:113], v[146:149], v[194:197], v[110:113]
	v_mfma_f32_16x16x32_bf16 v[106:109], v[162:165], v[194:197], v[106:109]
	v_mfma_f32_16x16x32_bf16 v[94:97], v[146:149], v[202:205], v[94:97]
	v_mfma_f32_16x16x32_bf16 v[90:93], v[162:165], v[202:205], v[90:93]
	v_mfma_f32_16x16x32_bf16 v[78:81], v[146:149], v[210:213], v[78:81]
	v_mfma_f32_16x16x32_bf16 v[74:77], v[162:165], v[210:213], v[74:77]
	s_setprio 0
	s_setprio 1
	v_mfma_f32_16x16x32_bf16 v[118:121], v[166:169], v[182:185], v[118:121]
	v_mfma_f32_16x16x32_bf16 v[114:117], v[174:177], v[182:185], v[114:117]
	v_mfma_f32_16x16x32_bf16 v[102:105], v[166:169], v[190:193], v[102:105]
	v_mfma_f32_16x16x32_bf16 v[98:101], v[174:177], v[190:193], v[98:101]
	v_mfma_f32_16x16x32_bf16 v[86:89], v[166:169], v[198:201], v[86:89]
	v_mfma_f32_16x16x32_bf16 v[82:85], v[174:177], v[198:201], v[82:85]
	v_mfma_f32_16x16x32_bf16 v[70:73], v[166:169], v[206:209], v[70:73]
	v_mfma_f32_16x16x32_bf16 v[66:69], v[174:177], v[206:209], v[66:69]
	v_mfma_f32_16x16x32_bf16 v[118:121], v[170:173], v[186:189], v[118:121]
	v_mfma_f32_16x16x32_bf16 v[114:117], v[178:181], v[186:189], v[114:117]
	v_mfma_f32_16x16x32_bf16 v[102:105], v[170:173], v[194:197], v[102:105]
	v_mfma_f32_16x16x32_bf16 v[98:101], v[178:181], v[194:197], v[98:101]
	v_mfma_f32_16x16x32_bf16 v[86:89], v[170:173], v[202:205], v[86:89]
	v_mfma_f32_16x16x32_bf16 v[82:85], v[178:181], v[202:205], v[82:85]
	v_mfma_f32_16x16x32_bf16 v[70:73], v[170:173], v[210:213], v[70:73]
	s_barrier
	v_mfma_f32_16x16x32_bf16 v[66:69], v[178:181], v[210:213], v[66:69]
	s_setprio 0
	s_add_i32 s61, s56, s33
	s_add_u32 s98, s46, s12
	s_addc_u32 s99, s47, s13
	s_mov_b32 m0, s61
	ds_read_b128 v[182:185], v161 offset:16384
	ds_read_b128 v[186:189], v161 offset:17408
	ds_read_b128 v[190:193], v161 offset:18432
	ds_read_b128 v[194:197], v161 offset:19456
	ds_read_b128 v[198:201], v161 offset:20480
	ds_read_b128 v[202:205], v161 offset:21504
	ds_read_b128 v[206:209], v161 offset:22528
	ds_read_b128 v[210:213], v161 offset:23552
	global_load_lds_dwordx4 v138, s[46:47]
	s_add_i32 m0, s61, 0x2000
	s_add_u32 s62, s46, 0x40000
	s_addc_u32 s63, s47, 0
	s_add_i32 s61, s57, s33
	global_load_lds_dwordx4 v134, s[46:47]
	s_mov_b32 m0, s61
	s_nop 0
	global_load_lds_dwordx4 v138, s[62:63]
	s_add_i32 m0, s61, 0x2000
	s_nop 0
	global_load_lds_dwordx4 v134, s[62:63]
	s_add_u32 s100, s48, s12
	s_addc_u32 s101, s49, s13
	s_mov_b32 m0, s50
	s_nop 0
	global_load_lds_dwordx4 v140, s[48:49]
	s_mov_b32 m0, s51
	s_nop 0
	global_load_lds_dwordx4 v136, s[48:49]
	s_waitcnt vmcnt(8)
	s_waitcnt lgkmcnt(0)
	s_barrier
	s_setprio 1
	s_waitcnt lgkmcnt(0)
	v_mfma_f32_16x16x32_bf16 v[62:65], v[130:133], v[182:185], v[62:65]
	v_mfma_f32_16x16x32_bf16 v[58:61], v[150:153], v[182:185], v[58:61]
	v_mfma_f32_16x16x32_bf16 v[46:49], v[130:133], v[190:193], v[46:49]
	v_mfma_f32_16x16x32_bf16 v[42:45], v[150:153], v[190:193], v[42:45]
	v_mfma_f32_16x16x32_bf16 v[30:33], v[130:133], v[198:201], v[30:33]
	v_mfma_f32_16x16x32_bf16 v[26:29], v[150:153], v[198:201], v[26:29]
	v_mfma_f32_16x16x32_bf16 v[14:17], v[130:133], v[206:209], v[14:17]
	v_mfma_f32_16x16x32_bf16 v[10:13], v[150:153], v[206:209], v[10:13]
	v_mfma_f32_16x16x32_bf16 v[62:65], v[146:149], v[186:189], v[62:65]
	v_mfma_f32_16x16x32_bf16 v[58:61], v[162:165], v[186:189], v[58:61]
	v_mfma_f32_16x16x32_bf16 v[46:49], v[146:149], v[194:197], v[46:49]
	v_mfma_f32_16x16x32_bf16 v[42:45], v[162:165], v[194:197], v[42:45]
	v_mfma_f32_16x16x32_bf16 v[30:33], v[146:149], v[202:205], v[30:33]
	v_mfma_f32_16x16x32_bf16 v[26:29], v[162:165], v[202:205], v[26:29]
	v_mfma_f32_16x16x32_bf16 v[14:17], v[146:149], v[210:213], v[14:17]
	v_mfma_f32_16x16x32_bf16 v[10:13], v[162:165], v[210:213], v[10:13]
	s_setprio 0
	s_setprio 1
	v_mfma_f32_16x16x32_bf16 v[54:57], v[166:169], v[182:185], v[54:57]
	v_mfma_f32_16x16x32_bf16 v[50:53], v[174:177], v[182:185], v[50:53]
	v_mfma_f32_16x16x32_bf16 v[38:41], v[166:169], v[190:193], v[38:41]
	v_mfma_f32_16x16x32_bf16 v[34:37], v[174:177], v[190:193], v[34:37]
	v_mfma_f32_16x16x32_bf16 v[22:25], v[166:169], v[198:201], v[22:25]
	v_mfma_f32_16x16x32_bf16 v[18:21], v[174:177], v[198:201], v[18:21]
	v_mfma_f32_16x16x32_bf16 v[6:9], v[166:169], v[206:209], v[6:9]
	v_mfma_f32_16x16x32_bf16 v[2:5], v[174:177], v[206:209], v[2:5]
	v_mfma_f32_16x16x32_bf16 v[54:57], v[170:173], v[186:189], v[54:57]
	v_mfma_f32_16x16x32_bf16 v[50:53], v[178:181], v[186:189], v[50:53]
	v_mfma_f32_16x16x32_bf16 v[38:41], v[170:173], v[194:197], v[38:41]
	v_mfma_f32_16x16x32_bf16 v[34:37], v[178:181], v[194:197], v[34:37]
	v_mfma_f32_16x16x32_bf16 v[22:25], v[170:173], v[202:205], v[22:25]
	v_mfma_f32_16x16x32_bf16 v[18:21], v[178:181], v[202:205], v[18:21]
	v_mfma_f32_16x16x32_bf16 v[6:9], v[170:173], v[210:213], v[6:9]
	s_barrier
; #define PG8_STAGE(bufoff, gbase, voff) do { _Pragma("unroll") for (int _i = 0; _i < 2; ++_i) \
;         __builtin_amdgcn_global_load_lds((const unsigned*)((const char*)(gbase) + (voff)[_i]), (PG8_LAS unsigned*)(lds + (bufoff) + ldsw + _i * 8192), 16, 0, 0); } while (0)
; #define PG8_LDA(dst, b, h) do { _Pragma("unroll") for (int m = 0; m < 4; ++m) _Pragma("unroll") for (int k = 0; k < 2; ++k) dst[m][k] = *(const PG8_LAS bf16x8*)(lds + PG8_SA(b, h) + aoff + m * 2048 + k * 1024); } while (0)
; #define PG8_LDB(dst, b, h) do { _Pragma("unroll") for (int n = 0; n < 2; ++n) _Pragma("unroll") for (int k = 0; k < 2; ++k) dst[n][k] = *(const PG8_LAS bf16x8*)(lds + PG8_SB(b, h) + boff + n * 2048 + k * 1024); } while (0)
; #define PG8_MMA(ai, bj, At, Bt) do { __builtin_amdgcn_s_setprio(1); _Pragma("unroll") for (int m = 0; m < 4; ++m) _Pragma("unroll") for (int n = 0; n < 2; ++n) _Pragma("unroll") for (int k = 0; k < 2; ++k) \
;         acc[ai][bj][m][n] = __builtin_amdgcn_mfma_f32_16x16x32_bf16(Bt[n][k], At[m][k], acc[ai][bj][m][n], 0, 0, 0); __builtin_amdgcn_s_setprio(0); } while (0)
; #define PG8_WAIT_V(n) asm volatile("s_waitcnt vmcnt(" #n ")" ::: "memory")
; #define PG8_WAIT_L(n) asm volatile("s_waitcnt lgkmcnt(" #n ")" ::: "memory")
; #define PG8_BAR __builtin_amdgcn_s_barrier()
; #define PG8_SCHED __builtin_amdgcn_sched_barrier(0)
; template <class Epi, class Sched, bool ALIGN_EPI = false, bool SP2 = false>
; __device__ __forceinline__ void gemm_phase(PG8_LAS unsigned char* lds, const Gemm g, const Sched& S, const Epi& E) {
;     ...
;             PG8_WAIT_V(8); PG8_WAIT_L(0); PG8_BAR; PG8_MMA(1, 0, At, B0); PG8_MMA(1, 1, At, B1); PG8_BAR; PG8_SCHED;
;             PG8_LDB(B0, 1, 0); PG8_LDB(B1, 1, 1); PG8_SCHED; PG8_LDA(At, 1, 0); PG8_STAGE(PG8_SA(0, 1), a2 + hstep, voffA);
;             PG8_WAIT_V(8); PG8_WAIT_L(0); PG8_BAR; PG8_MMA(0, 0, At, B0); PG8_MMA(0, 1, At, B1); PG8_BAR; PG8_SCHED;
;             PG8_LDA(At, 1, 1); PG8_STAGE(PG8_SB(1, 0), b3, voffB); PG8_STAGE(PG8_SB(1, 1), b3 + hstep, voffB); PG8_STAGE(PG8_SA(1, 0), a3, voffA);
;             PG8_WAIT_V(8); PG8_WAIT_L(0); PG8_BAR; PG8_MMA(1, 0, At, B0); PG8_MMA(1, 1, At, B1); PG8_BAR; PG8_SCHED;
	v_mfma_f32_16x16x32_bf16 v[2:5], v[178:181], v[210:213], v[2:5]
	s_setprio 0
	s_add_i32 s61, 0, 0x18000
	s_add_i32 s62, 0, 0x1c000
	v_add_u32_e32 v162, s61, v155
	v_add_u32_e32 v178, s62, v155
	ds_read_b128 v[130:133], v162
	ds_read_b128 v[146:149], v162 offset:1024
	ds_read_b128 v[150:153], v162 offset:2048
	ds_read_b128 v[162:165], v162 offset:3072
	ds_read_b128 v[166:169], v178
	ds_read_b128 v[170:173], v178 offset:1024
	ds_read_b128 v[174:177], v178 offset:2048
	ds_read_b128 v[178:181], v178 offset:3072
	s_add_u32 s48, s48, 0x40000
	s_addc_u32 s49, s49, 0
	s_mov_b32 m0, s52
	ds_read_b128 v[182:185], v161 offset:32768
	ds_read_b128 v[186:189], v161 offset:33792
	ds_read_b128 v[190:193], v161 offset:34816
	ds_read_b128 v[194:197], v161 offset:35840
	ds_read_b128 v[198:201], v161 offset:36864
	ds_read_b128 v[202:205], v161 offset:37888
	ds_read_b128 v[206:209], v161 offset:38912
	ds_read_b128 v[210:213], v161 offset:39936
	global_load_lds_dwordx4 v140, s[48:49]
	s_mov_b32 m0, s53
	s_nop 0
	global_load_lds_dwordx4 v136, s[48:49]
	s_waitcnt vmcnt(8)
	s_waitcnt lgkmcnt(0)
	s_barrier
	s_setprio 1
	s_waitcnt lgkmcnt(0)
	v_mfma_f32_16x16x32_bf16 v[126:129], v[130:133], v[182:185], v[126:129]
	v_mfma_f32_16x16x32_bf16 v[122:125], v[150:153], v[182:185], v[122:125]
	v_mfma_f32_16x16x32_bf16 v[110:113], v[130:133], v[190:193], v[110:113]
	v_mfma_f32_16x16x32_bf16 v[106:109], v[150:153], v[190:193], v[106:109]
	v_mfma_f32_16x16x32_bf16 v[94:97], v[130:133], v[198:201], v[94:97]
	v_mfma_f32_16x16x32_bf16 v[90:93], v[150:153], v[198:201], v[90:93]
	v_mfma_f32_16x16x32_bf16 v[78:81], v[130:133], v[206:209], v[78:81]
	v_mfma_f32_16x16x32_bf16 v[74:77], v[150:153], v[206:209], v[74:77]
	v_mfma_f32_16x16x32_bf16 v[126:129], v[146:149], v[186:189], v[126:129]
	v_mfma_f32_16x16x32_bf16 v[122:125], v[162:165], v[186:189], v[122:125]
	v_mfma_f32_16x16x32_bf16 v[110:113], v[146:149], v[194:197], v[110:113]
	v_mfma_f32_16x16x32_bf16 v[106:109], v[162:165], v[194:197], v[106:109]
	v_mfma_f32_16x16x32_bf16 v[94:97], v[146:149], v[202:205], v[94:97]
	v_mfma_f32_16x16x32_bf16 v[90:93], v[162:165], v[202:205], v[90:93]
	v_mfma_f32_16x16x32_bf16 v[78:81], v[146:149], v[210:213], v[78:81]
	v_mfma_f32_16x16x32_bf16 v[74:77], v[162:165], v[210:213], v[74:77]
	s_setprio 0
	s_setprio 1
	v_mfma_f32_16x16x32_bf16 v[118:121], v[166:169], v[182:185], v[118:121]
	v_mfma_f32_16x16x32_bf16 v[114:117], v[174:177], v[182:185], v[114:117]
	v_mfma_f32_16x16x32_bf16 v[102:105], v[166:169], v[190:193], v[102:105]
	v_mfma_f32_16x16x32_bf16 v[98:101], v[174:177], v[190:193], v[98:101]
	v_mfma_f32_16x16x32_bf16 v[86:89], v[166:169], v[198:201], v[86:89]
	v_mfma_f32_16x16x32_bf16 v[82:85], v[174:177], v[198:201], v[82:85]
	v_mfma_f32_16x16x32_bf16 v[70:73], v[166:169], v[206:209], v[70:73]
	v_mfma_f32_16x16x32_bf16 v[66:69], v[174:177], v[206:209], v[66:69]
	v_mfma_f32_16x16x32_bf16 v[118:121], v[170:173], v[186:189], v[118:121]
	v_mfma_f32_16x16x32_bf16 v[114:117], v[178:181], v[186:189], v[114:117]
	v_mfma_f32_16x16x32_bf16 v[102:105], v[170:173], v[194:197], v[102:105]
	v_mfma_f32_16x16x32_bf16 v[98:101], v[178:181], v[194:197], v[98:101]
	v_mfma_f32_16x16x32_bf16 v[86:89], v[170:173], v[202:205], v[86:89]
	v_mfma_f32_16x16x32_bf16 v[82:85], v[178:181], v[202:205], v[82:85]
	v_mfma_f32_16x16x32_bf16 v[70:73], v[170:173], v[210:213], v[70:73]
	s_barrier
	v_mfma_f32_16x16x32_bf16 v[66:69], v[178:181], v[210:213], v[66:69]
	s_setprio 0
	s_add_i32 s48, s61, s33
	s_mov_b32 m0, s48
	ds_read_b128 v[182:185], v161 offset:49152
	ds_read_b128 v[186:189], v161 offset:50176
	ds_read_b128 v[190:193], v161 offset:51200
	ds_read_b128 v[194:197], v161 offset:52224
	ds_read_b128 v[198:201], v161 offset:53248
	ds_read_b128 v[202:205], v161 offset:54272
	ds_read_b128 v[206:209], v161 offset:55296
	ds_read_b128 v[210:213], v161 offset:56320
	global_load_lds_dwordx4 v138, s[98:99]
	s_add_i32 m0, s48, 0x2000
	s_add_u32 s46, s46, 0x40080
	s_addc_u32 s47, s47, 0
	s_add_i32 s48, s62, s33
	global_load_lds_dwordx4 v134, s[98:99]
	s_mov_b32 m0, s48
	s_nop 0
	global_load_lds_dwordx4 v138, s[46:47]
	s_add_i32 m0, s48, 0x2000
	s_nop 0
	global_load_lds_dwordx4 v134, s[46:47]
	s_mov_b32 m0, s54
	s_nop 0
	global_load_lds_dwordx4 v140, s[100:101]
	s_mov_b32 m0, s55
	s_nop 0
	global_load_lds_dwordx4 v136, s[100:101]
	s_waitcnt vmcnt(8)
	s_waitcnt lgkmcnt(0)
	s_barrier
	s_setprio 1
	s_waitcnt lgkmcnt(0)
	v_mfma_f32_16x16x32_bf16 v[62:65], v[130:133], v[182:185], v[62:65]
	v_mfma_f32_16x16x32_bf16 v[58:61], v[150:153], v[182:185], v[58:61]
	v_mfma_f32_16x16x32_bf16 v[46:49], v[130:133], v[190:193], v[46:49]
	v_mfma_f32_16x16x32_bf16 v[42:45], v[150:153], v[190:193], v[42:45]
	v_mfma_f32_16x16x32_bf16 v[30:33], v[130:133], v[198:201], v[30:33]
	v_mfma_f32_16x16x32_bf16 v[26:29], v[150:153], v[198:201], v[26:29]
	v_mfma_f32_16x16x32_bf16 v[14:17], v[130:133], v[206:209], v[14:17]
	v_mfma_f32_16x16x32_bf16 v[10:13], v[150:153], v[206:209], v[10:13]
	v_mfma_f32_16x16x32_bf16 v[62:65], v[146:149], v[186:189], v[62:65]
	v_mfma_f32_16x16x32_bf16 v[58:61], v[162:165], v[186:189], v[58:61]
	v_mfma_f32_16x16x32_bf16 v[46:49], v[146:149], v[194:197], v[46:49]
	v_mfma_f32_16x16x32_bf16 v[42:45], v[162:165], v[194:197], v[42:45]
	v_mfma_f32_16x16x32_bf16 v[30:33], v[146:149], v[202:205], v[30:33]
	v_mfma_f32_16x16x32_bf16 v[26:29], v[162:165], v[202:205], v[26:29]
	v_mfma_f32_16x16x32_bf16 v[14:17], v[146:149], v[210:213], v[14:17]
	v_mfma_f32_16x16x32_bf16 v[10:13], v[162:165], v[210:213], v[10:13]
	s_setprio 0
	s_setprio 1
	v_mfma_f32_16x16x32_bf16 v[54:57], v[166:169], v[182:185], v[54:57]
	v_mfma_f32_16x16x32_bf16 v[50:53], v[174:177], v[182:185], v[50:53]
	v_mfma_f32_16x16x32_bf16 v[38:41], v[166:169], v[190:193], v[38:41]
	v_mfma_f32_16x16x32_bf16 v[34:37], v[174:177], v[190:193], v[34:37]
	v_mfma_f32_16x16x32_bf16 v[22:25], v[166:169], v[198:201], v[22:25]
	v_mfma_f32_16x16x32_bf16 v[18:21], v[174:177], v[198:201], v[18:21]
	v_mfma_f32_16x16x32_bf16 v[6:9], v[166:169], v[206:209], v[6:9]
	v_mfma_f32_16x16x32_bf16 v[2:5], v[174:177], v[206:209], v[2:5]
	v_mfma_f32_16x16x32_bf16 v[54:57], v[170:173], v[186:189], v[54:57]
	v_mfma_f32_16x16x32_bf16 v[50:53], v[178:181], v[186:189], v[50:53]
	v_mfma_f32_16x16x32_bf16 v[38:41], v[170:173], v[194:197], v[38:41]
	v_mfma_f32_16x16x32_bf16 v[34:37], v[178:181], v[194:197], v[34:37]
	v_mfma_f32_16x16x32_bf16 v[22:25], v[170:173], v[202:205], v[22:25]
	v_mfma_f32_16x16x32_bf16 v[18:21], v[178:181], v[202:205], v[18:21]
	v_mfma_f32_16x16x32_bf16 v[6:9], v[170:173], v[210:213], v[6:9]
	s_barrier
	v_mfma_f32_16x16x32_bf16 v[2:5], v[178:181], v[210:213], v[2:5]
	s_setprio 0
	s_add_i32 s60, s60, 2
	s_add_u32 s44, s44, 0x100
	s_addc_u32 s45, s45, 0
	s_add_u32 s58, s58, 0x100
	s_addc_u32 s59, s59, 0
	s_cmp_gt_u32 s60, 13
	s_cbranch_scc0 .LBB0_884
	s_nop 0
	s_and_b64 vcc, exec, s[14:15]
	s_cbranch_vccz .LBB0_887
	s_barrier

; #define PG8_STAGE(bufoff, gbase, voff) do { _Pragma("unroll") for (int _i = 0; _i < 2; ++_i) \
;         __builtin_amdgcn_global_load_lds((const unsigned*)((const char*)(gbase) + (voff)[_i]), (PG8_LAS unsigned*)(lds + (bufoff) + ldsw + _i * 8192), 16, 0, 0); } while (0)
; #define PG8_LDA(dst, b, h) do { _Pragma("unroll") for (int m = 0; m < 4; ++m) _Pragma("unroll") for (int k = 0; k < 2; ++k) dst[m][k] = *(const PG8_LAS bf16x8*)(lds + PG8_SA(b, h) + aoff + m * 2048 + k * 1024); } while (0)
; #define PG8_LDB(dst, b, h) do { _Pragma("unroll") for (int n = 0; n < 2; ++n) _Pragma("unroll") for (int k = 0; k < 2; ++k) dst[n][k] = *(const PG8_LAS bf16x8*)(lds + PG8_SB(b, h) + boff + n * 2048 + k * 1024); } while (0)
; #define PG8_MMA(ai, bj, At, Bt) do { __builtin_amdgcn_s_setprio(1); _Pragma("unroll") for (int m = 0; m < 4; ++m) _Pragma("unroll") for (int n = 0; n < 2; ++n) _Pragma("unroll") for (int k = 0; k < 2; ++k) \
;         acc[ai][bj][m][n] = __builtin_amdgcn_mfma_f32_16x16x32_bf16(Bt[n][k], At[m][k], acc[ai][bj][m][n], 0, 0, 0); __builtin_amdgcn_s_setprio(0); } while (0)
; #define PG8_WAIT_V(n) asm volatile("s_waitcnt vmcnt(" #n ")" ::: "memory")
; #define PG8_WAIT_L(n) asm volatile("s_waitcnt lgkmcnt(" #n ")" ::: "memory")
; #define PG8_BAR __builtin_amdgcn_s_barrier()
; #define PG8_SCHED __builtin_amdgcn_sched_barrier(0)
; template <class Epi, class Sched, bool ALIGN_EPI = false, bool SP2 = false>
; __device__ __forceinline__ void gemm_phase(PG8_LAS unsigned char* lds, const Gemm g, const Sched& S, const Epi& E) {
;     ...
;             const bool last = (t == nt - 2);
;             const char* a1 = cA + (size_t)(t + 1) * kstep;
;             const char* a2 = last ? nA : cA + (size_t)(t + 2) * kstep; const char* b2 = last ? nB : cB + (size_t)(t + 2) * kstep;
;             const char* a3 = a2 + kstep; const char* b3 = b2 + kstep;
;             if (last && has_next) S.a_ready(nxt);
;             if constexpr (SP2) {
;             PG8_LDB(B0, 0, 0); PG8_LDB(B1, 0, 1); PG8_SCHED; PG8_LDA(At, 0, 0); PG8_STAGE(PG8_SA(1, 1), a1 + hstep, voffA);
;             PG8_WAIT_V(8); PG8_WAIT_L(0); PG8_BAR; PG8_MMA(0, 0, At, B0); PG8_MMA(0, 1, At, B1); PG8_BAR; PG8_SCHED;
;             PG8_LDA(At, 0, 1); PG8_STAGE(PG8_SB(0, 0), b2, voffB); PG8_STAGE(PG8_SB(0, 1), b2 + hstep, voffB); PG8_STAGE(PG8_SA(0, 0), a2, voffA);
.LBB0_968:
	v_add_u32_e32 v162, s45, v148
	v_add_u32_e32 v178, s46, v148
	s_add_u32 s22, s8, s20
	ds_read_b128 v[150:153], v162
	ds_read_b128 v[154:157], v162 offset:1024
	ds_read_b128 v[158:161], v162 offset:2048
	ds_read_b128 v[162:165], v162 offset:3072
	ds_read_b128 v[166:169], v178
	ds_read_b128 v[170:173], v178 offset:1024
	ds_read_b128 v[174:177], v178 offset:2048
	ds_read_b128 v[178:181], v178 offset:3072
	s_addc_u32 s23, s9, s21
	s_add_u32 s22, s22, 0x100
	s_addc_u32 s23, s23, 0
	s_add_u32 s51, s48, s20
	s_addc_u32 s52, s49, s21
	s_cmpk_eq_i32 s20, 0x700
	s_cselect_b32 s25, s19, s23
	s_cselect_b32 s24, s18, s22
	s_cselect_b32 s23, s13, s52
	s_cselect_b32 s22, s15, s51
	v_lshl_add_u64 v[214:215], v[142:143], 0, s[20:21]
	s_add_i32 m0, s5, 0xc000
	ds_read_b128 v[182:185], v149
	ds_read_b128 v[186:189], v149 offset:1024
	ds_read_b128 v[190:193], v149 offset:2048
	ds_read_b128 v[194:197], v149 offset:3072
	ds_read_b128 v[198:201], v149 offset:4096
	ds_read_b128 v[202:205], v149 offset:5120
	ds_read_b128 v[206:209], v149 offset:6144
	ds_read_b128 v[210:213], v149 offset:7168
	global_load_lds_dwordx4 v[214:215], off
	v_lshl_add_u64 v[214:215], v[144:145], 0, s[20:21]
	s_add_i32 m0, s5, 0xe000
	s_nop 0
	global_load_lds_dwordx4 v[214:215], off
	s_waitcnt vmcnt(8)
	s_waitcnt lgkmcnt(0)
	s_barrier
	s_setprio 1
	s_waitcnt lgkmcnt(0)
	v_mfma_f32_16x16x32_bf16 v[126:129], v[150:153], v[182:185], v[126:129]
	v_mfma_f32_16x16x32_bf16 v[122:125], v[158:161], v[182:185], v[122:125]
	v_mfma_f32_16x16x32_bf16 v[114:117], v[150:153], v[190:193], v[114:117]
	v_mfma_f32_16x16x32_bf16 v[106:109], v[158:161], v[190:193], v[106:109]
	v_mfma_f32_16x16x32_bf16 v[98:101], v[150:153], v[198:201], v[98:101]
	v_mfma_f32_16x16x32_bf16 v[90:93], v[158:161], v[198:201], v[90:93]
	v_mfma_f32_16x16x32_bf16 v[82:85], v[150:153], v[206:209], v[82:85]
	v_mfma_f32_16x16x32_bf16 v[74:77], v[158:161], v[206:209], v[74:77]
	v_mfma_f32_16x16x32_bf16 v[126:129], v[154:157], v[186:189], v[126:129]
	v_mfma_f32_16x16x32_bf16 v[122:125], v[162:165], v[186:189], v[122:125]
	v_mfma_f32_16x16x32_bf16 v[114:117], v[154:157], v[194:197], v[114:117]
	v_mfma_f32_16x16x32_bf16 v[106:109], v[162:165], v[194:197], v[106:109]
	v_mfma_f32_16x16x32_bf16 v[98:101], v[154:157], v[202:205], v[98:101]
	v_mfma_f32_16x16x32_bf16 v[90:93], v[162:165], v[202:205], v[90:93]
	v_mfma_f32_16x16x32_bf16 v[82:85], v[154:157], v[210:213], v[82:85]
	v_mfma_f32_16x16x32_bf16 v[74:77], v[162:165], v[210:213], v[74:77]
	s_setprio 0
	s_setprio 1
	v_mfma_f32_16x16x32_bf16 v[118:121], v[166:169], v[182:185], v[118:121]
	v_mfma_f32_16x16x32_bf16 v[110:113], v[174:177], v[182:185], v[110:113]
	v_mfma_f32_16x16x32_bf16 v[102:105], v[166:169], v[190:193], v[102:105]
	v_mfma_f32_16x16x32_bf16 v[94:97], v[174:177], v[190:193], v[94:97]
	v_mfma_f32_16x16x32_bf16 v[86:89], v[166:169], v[198:201], v[86:89]
	v_mfma_f32_16x16x32_bf16 v[78:81], v[174:177], v[198:201], v[78:81]
	v_mfma_f32_16x16x32_bf16 v[70:73], v[166:169], v[206:209], v[70:73]
	v_mfma_f32_16x16x32_bf16 v[66:69], v[174:177], v[206:209], v[66:69]
	v_mfma_f32_16x16x32_bf16 v[118:121], v[170:173], v[186:189], v[118:121]
	v_mfma_f32_16x16x32_bf16 v[110:113], v[178:181], v[186:189], v[110:113]
	v_mfma_f32_16x16x32_bf16 v[102:105], v[170:173], v[194:197], v[102:105]
	v_mfma_f32_16x16x32_bf16 v[94:97], v[178:181], v[194:197], v[94:97]
	v_mfma_f32_16x16x32_bf16 v[86:89], v[170:173], v[202:205], v[86:89]
	v_mfma_f32_16x16x32_bf16 v[78:81], v[178:181], v[202:205], v[78:81]
	v_mfma_f32_16x16x32_bf16 v[70:73], v[170:173], v[210:213], v[70:73]
	s_barrier
	v_mfma_f32_16x16x32_bf16 v[66:69], v[178:181], v[210:213], v[66:69]
	s_setprio 0
	s_add_i32 s51, s45, s38
	s_add_u32 s98, s22, s10
	s_addc_u32 s99, s23, s11
	s_mov_b32 m0, s51
	ds_read_b128 v[182:185], v149 offset:16384
	ds_read_b128 v[186:189], v149 offset:17408
	ds_read_b128 v[190:193], v149 offset:18432
	ds_read_b128 v[194:197], v149 offset:19456
	ds_read_b128 v[198:201], v149 offset:20480
	ds_read_b128 v[202:205], v149 offset:21504
	ds_read_b128 v[206:209], v149 offset:22528
	ds_read_b128 v[210:213], v149 offset:23552
	global_load_lds_dwordx4 v130, s[22:23]
	s_add_i32 m0, s51, 0x2000
	s_add_u32 s52, s22, 0x40000
	s_addc_u32 s53, s23, 0
	s_add_i32 s51, s46, s38
	global_load_lds_dwordx4 v132, s[22:23]
	s_mov_b32 m0, s51
	s_nop 0
	global_load_lds_dwordx4 v130, s[52:53]
	s_add_i32 m0, s51, 0x2000
	s_nop 0
	global_load_lds_dwordx4 v132, s[52:53]
	s_add_u32 s100, s24, s10
	s_addc_u32 s101, s25, s11
	s_mov_b32 m0, s5
	s_nop 0
	global_load_lds_dwordx4 v130, s[24:25]
	s_mov_b32 m0, s39
	s_nop 0
	global_load_lds_dwordx4 v132, s[24:25]
	s_waitcnt vmcnt(8)
	s_waitcnt lgkmcnt(0)
	s_barrier
; #define PG8_STAGE(bufoff, gbase, voff) do { _Pragma("unroll") for (int _i = 0; _i < 2; ++_i) \
;         __builtin_amdgcn_global_load_lds((const unsigned*)((const char*)(gbase) + (voff)[_i]), (PG8_LAS unsigned*)(lds + (bufoff) + ldsw + _i * 8192), 16, 0, 0); } while (0)
; #define PG8_LDA(dst, b, h) do { _Pragma("unroll") for (int m = 0; m < 4; ++m) _Pragma("unroll") for (int k = 0; k < 2; ++k) dst[m][k] = *(const PG8_LAS bf16x8*)(lds + PG8_SA(b, h) + aoff + m * 2048 + k * 1024); } while (0)
; #define PG8_LDB(dst, b, h) do { _Pragma("unroll") for (int n = 0; n < 2; ++n) _Pragma("unroll") for (int k = 0; k < 2; ++k) dst[n][k] = *(const PG8_LAS bf16x8*)(lds + PG8_SB(b, h) + boff + n * 2048 + k * 1024); } while (0)
; #define PG8_MMA(ai, bj, At, Bt) do { __builtin_amdgcn_s_setprio(1); _Pragma("unroll") for (int m = 0; m < 4; ++m) _Pragma("unroll") for (int n = 0; n < 2; ++n) _Pragma("unroll") for (int k = 0; k < 2; ++k) \
;         acc[ai][bj][m][n] = __builtin_amdgcn_mfma_f32_16x16x32_bf16(Bt[n][k], At[m][k], acc[ai][bj][m][n], 0, 0, 0); __builtin_amdgcn_s_setprio(0); } while (0)
; #define PG8_WAIT_V(n) asm volatile("s_waitcnt vmcnt(" #n ")" ::: "memory")
; #define PG8_WAIT_L(n) asm volatile("s_waitcnt lgkmcnt(" #n ")" ::: "memory")
; #define PG8_BAR __builtin_amdgcn_s_barrier()
; #define PG8_SCHED __builtin_amdgcn_sched_barrier(0)
; template <class Epi, class Sched, bool ALIGN_EPI = false, bool SP2 = false>
; __device__ __forceinline__ void gemm_phase(PG8_LAS unsigned char* lds, const Gemm g, const Sched& S, const Epi& E) {
;     ...
;             PG8_WAIT_V(8); PG8_WAIT_L(0); PG8_BAR; PG8_MMA(1, 0, At, B0); PG8_MMA(1, 1, At, B1); PG8_BAR; PG8_SCHED;
;             PG8_LDB(B0, 1, 0); PG8_LDB(B1, 1, 1); PG8_SCHED; PG8_LDA(At, 1, 0); PG8_STAGE(PG8_SA(0, 1), a2 + hstep, voffA);
;             PG8_WAIT_V(8); PG8_WAIT_L(0); PG8_BAR; PG8_MMA(0, 0, At, B0); PG8_MMA(0, 1, At, B1); PG8_BAR; PG8_SCHED;
	s_setprio 1
	s_waitcnt lgkmcnt(0)
	v_mfma_f32_16x16x32_bf16 v[62:65], v[150:153], v[182:185], v[62:65]
	v_mfma_f32_16x16x32_bf16 v[58:61], v[158:161], v[182:185], v[58:61]
	v_mfma_f32_16x16x32_bf16 v[50:53], v[150:153], v[190:193], v[50:53]
	v_mfma_f32_16x16x32_bf16 v[42:45], v[158:161], v[190:193], v[42:45]
	v_mfma_f32_16x16x32_bf16 v[34:37], v[150:153], v[198:201], v[34:37]
	v_mfma_f32_16x16x32_bf16 v[26:29], v[158:161], v[198:201], v[26:29]
	v_mfma_f32_16x16x32_bf16 v[18:21], v[150:153], v[206:209], v[18:21]
	v_mfma_f32_16x16x32_bf16 v[10:13], v[158:161], v[206:209], v[10:13]
	v_mfma_f32_16x16x32_bf16 v[62:65], v[154:157], v[186:189], v[62:65]
	v_mfma_f32_16x16x32_bf16 v[58:61], v[162:165], v[186:189], v[58:61]
	v_mfma_f32_16x16x32_bf16 v[50:53], v[154:157], v[194:197], v[50:53]
	v_mfma_f32_16x16x32_bf16 v[42:45], v[162:165], v[194:197], v[42:45]
	v_mfma_f32_16x16x32_bf16 v[34:37], v[154:157], v[202:205], v[34:37]
	v_mfma_f32_16x16x32_bf16 v[26:29], v[162:165], v[202:205], v[26:29]
	v_mfma_f32_16x16x32_bf16 v[18:21], v[154:157], v[210:213], v[18:21]
	v_mfma_f32_16x16x32_bf16 v[10:13], v[162:165], v[210:213], v[10:13]
	s_setprio 0
	s_setprio 1
	v_mfma_f32_16x16x32_bf16 v[54:57], v[166:169], v[182:185], v[54:57]
	v_mfma_f32_16x16x32_bf16 v[46:49], v[174:177], v[182:185], v[46:49]
	v_mfma_f32_16x16x32_bf16 v[38:41], v[166:169], v[190:193], v[38:41]
	v_mfma_f32_16x16x32_bf16 v[30:33], v[174:177], v[190:193], v[30:33]
	v_mfma_f32_16x16x32_bf16 v[22:25], v[166:169], v[198:201], v[22:25]
	v_mfma_f32_16x16x32_bf16 v[14:17], v[174:177], v[198:201], v[14:17]
	v_mfma_f32_16x16x32_bf16 v[6:9], v[166:169], v[206:209], v[6:9]
	v_mfma_f32_16x16x32_bf16 v[2:5], v[174:177], v[206:209], v[2:5]
	v_mfma_f32_16x16x32_bf16 v[54:57], v[170:173], v[186:189], v[54:57]
	v_mfma_f32_16x16x32_bf16 v[46:49], v[178:181], v[186:189], v[46:49]
	v_mfma_f32_16x16x32_bf16 v[38:41], v[170:173], v[194:197], v[38:41]
	v_mfma_f32_16x16x32_bf16 v[30:33], v[178:181], v[194:197], v[30:33]
	v_mfma_f32_16x16x32_bf16 v[22:25], v[170:173], v[202:205], v[22:25]
	v_mfma_f32_16x16x32_bf16 v[14:17], v[178:181], v[202:205], v[14:17]
	v_mfma_f32_16x16x32_bf16 v[6:9], v[170:173], v[210:213], v[6:9]
	s_barrier
	v_mfma_f32_16x16x32_bf16 v[2:5], v[178:181], v[210:213], v[2:5]
	s_setprio 0
	s_add_i32 s51, 0, 0x18000
	s_add_i32 s52, 0, 0x1c000
	v_add_u32_e32 v162, s51, v148
	v_add_u32_e32 v178, s52, v148
	ds_read_b128 v[150:153], v162
	ds_read_b128 v[154:157], v162 offset:1024
	ds_read_b128 v[158:161], v162 offset:2048
	ds_read_b128 v[162:165], v162 offset:3072
	ds_read_b128 v[166:169], v178
	ds_read_b128 v[170:173], v178 offset:1024
	ds_read_b128 v[174:177], v178 offset:2048
	ds_read_b128 v[178:181], v178 offset:3072
	s_add_u32 s24, s24, 0x40000
	s_addc_u32 s25, s25, 0
	s_mov_b32 m0, s40
	ds_read_b128 v[182:185], v149 offset:32768
	ds_read_b128 v[186:189], v149 offset:33792
	ds_read_b128 v[190:193], v149 offset:34816
	ds_read_b128 v[194:197], v149 offset:35840
	ds_read_b128 v[198:201], v149 offset:36864
	ds_read_b128 v[202:205], v149 offset:37888
	ds_read_b128 v[206:209], v149 offset:38912
	ds_read_b128 v[210:213], v149 offset:39936
	global_load_lds_dwordx4 v130, s[24:25]
	s_mov_b32 m0, s41
	s_nop 0
	global_load_lds_dwordx4 v132, s[24:25]
	s_waitcnt vmcnt(8)
	s_waitcnt lgkmcnt(0)
	s_barrier
	s_setprio 1
	s_waitcnt lgkmcnt(0)
	v_mfma_f32_16x16x32_bf16 v[126:129], v[150:153], v[182:185], v[126:129]
	v_mfma_f32_16x16x32_bf16 v[122:125], v[158:161], v[182:185], v[122:125]
	v_mfma_f32_16x16x32_bf16 v[114:117], v[150:153], v[190:193], v[114:117]
	v_mfma_f32_16x16x32_bf16 v[106:109], v[158:161], v[190:193], v[106:109]
	v_mfma_f32_16x16x32_bf16 v[98:101], v[150:153], v[198:201], v[98:101]
	v_mfma_f32_16x16x32_bf16 v[90:93], v[158:161], v[198:201], v[90:93]
	v_mfma_f32_16x16x32_bf16 v[82:85], v[150:153], v[206:209], v[82:85]
	v_mfma_f32_16x16x32_bf16 v[74:77], v[158:161], v[206:209], v[74:77]
	v_mfma_f32_16x16x32_bf16 v[126:129], v[154:157], v[186:189], v[126:129]
	v_mfma_f32_16x16x32_bf16 v[122:125], v[162:165], v[186:189], v[122:125]
	v_mfma_f32_16x16x32_bf16 v[114:117], v[154:157], v[194:197], v[114:117]
	v_mfma_f32_16x16x32_bf16 v[106:109], v[162:165], v[194:197], v[106:109]
	v_mfma_f32_16x16x32_bf16 v[98:101], v[154:157], v[202:205], v[98:101]
	v_mfma_f32_16x16x32_bf16 v[90:93], v[162:165], v[202:205], v[90:93]
	v_mfma_f32_16x16x32_bf16 v[82:85], v[154:157], v[210:213], v[82:85]
	v_mfma_f32_16x16x32_bf16 v[74:77], v[162:165], v[210:213], v[74:77]
	s_setprio 0
	s_setprio 1
	v_mfma_f32_16x16x32_bf16 v[118:121], v[166:169], v[182:185], v[118:121]
	v_mfma_f32_16x16x32_bf16 v[110:113], v[174:177], v[182:185], v[110:113]
	v_mfma_f32_16x16x32_bf16 v[102:105], v[166:169], v[190:193], v[102:105]
	v_mfma_f32_16x16x32_bf16 v[94:97], v[174:177], v[190:193], v[94:97]
	v_mfma_f32_16x16x32_bf16 v[86:89], v[166:169], v[198:201], v[86:89]
	v_mfma_f32_16x16x32_bf16 v[78:81], v[174:177], v[198:201], v[78:81]
	v_mfma_f32_16x16x32_bf16 v[70:73], v[166:169], v[206:209], v[70:73]
	v_mfma_f32_16x16x32_bf16 v[66:69], v[174:177], v[206:209], v[66:69]
	v_mfma_f32_16x16x32_bf16 v[118:121], v[170:173], v[186:189], v[118:121]
	v_mfma_f32_16x16x32_bf16 v[110:113], v[178:181], v[186:189], v[110:113]
	v_mfma_f32_16x16x32_bf16 v[102:105], v[170:173], v[194:197], v[102:105]
	v_mfma_f32_16x16x32_bf16 v[94:97], v[178:181], v[194:197], v[94:97]
	v_mfma_f32_16x16x32_bf16 v[86:89], v[170:173], v[202:205], v[86:89]
	v_mfma_f32_16x16x32_bf16 v[78:81], v[178:181], v[202:205], v[78:81]
	v_mfma_f32_16x16x32_bf16 v[70:73], v[170:173], v[210:213], v[70:73]
	s_barrier
; #define PG8_STAGE(bufoff, gbase, voff) do { _Pragma("unroll") for (int _i = 0; _i < 2; ++_i) \
;         __builtin_amdgcn_global_load_lds((const unsigned*)((const char*)(gbase) + (voff)[_i]), (PG8_LAS unsigned*)(lds + (bufoff) + ldsw + _i * 8192), 16, 0, 0); } while (0)
; #define PG8_LDA(dst, b, h) do { _Pragma("unroll") for (int m = 0; m < 4; ++m) _Pragma("unroll") for (int k = 0; k < 2; ++k) dst[m][k] = *(const PG8_LAS bf16x8*)(lds + PG8_SA(b, h) + aoff + m * 2048 + k * 1024); } while (0)
; #define PG8_MMA(ai, bj, At, Bt) do { __builtin_amdgcn_s_setprio(1); _Pragma("unroll") for (int m = 0; m < 4; ++m) _Pragma("unroll") for (int n = 0; n < 2; ++n) _Pragma("unroll") for (int k = 0; k < 2; ++k) \
;         acc[ai][bj][m][n] = __builtin_amdgcn_mfma_f32_16x16x32_bf16(Bt[n][k], At[m][k], acc[ai][bj][m][n], 0, 0, 0); __builtin_amdgcn_s_setprio(0); } while (0)
; #define PG8_WAIT_V(n) asm volatile("s_waitcnt vmcnt(" #n ")" ::: "memory")
; #define PG8_WAIT_L(n) asm volatile("s_waitcnt lgkmcnt(" #n ")" ::: "memory")
; #define PG8_BAR __builtin_amdgcn_s_barrier()
; #define PG8_SCHED __builtin_amdgcn_sched_barrier(0)
; template <class Epi, class Sched, bool ALIGN_EPI = false, bool SP2 = false>
; __device__ __forceinline__ void gemm_phase(PG8_LAS unsigned char* lds, const Gemm g, const Sched& S, const Epi& E) {
;     ...
;             PG8_WAIT_V(8); PG8_WAIT_L(0); PG8_BAR; PG8_MMA(0, 0, At, B0); PG8_MMA(0, 1, At, B1); PG8_BAR; PG8_SCHED;
;             PG8_LDA(At, 1, 1); PG8_STAGE(PG8_SB(1, 0), b3, voffB); PG8_STAGE(PG8_SB(1, 1), b3 + hstep, voffB); PG8_STAGE(PG8_SA(1, 0), a3, voffA);
;             PG8_WAIT_V(8); PG8_WAIT_L(0); PG8_BAR; PG8_MMA(1, 0, At, B0); PG8_MMA(1, 1, At, B1); PG8_BAR; PG8_SCHED;
;     ...
;         if (!has_next) break;
; #pragma unroll
;         for (int a = 0; a < 2; ++a)
; #pragma unroll
;             for (int b = 0; b < 2; ++b)
; #pragma unroll
;                 for (int m = 0; m < 4; ++m)
; #pragma unroll
;                     for (int n = 0; n < 2; ++n) acc[a][b][m][n] = (f32x4){0.f, 0.f, 0.f, 0.f};
;         cur = nxt; cA = nA; cB = nB; ++ui;
	v_mfma_f32_16x16x32_bf16 v[66:69], v[178:181], v[210:213], v[66:69]
	s_setprio 0
	s_add_i32 s24, s51, s38
	s_mov_b32 m0, s24
	ds_read_b128 v[182:185], v149 offset:49152
	ds_read_b128 v[186:189], v149 offset:50176
	ds_read_b128 v[190:193], v149 offset:51200
	ds_read_b128 v[194:197], v149 offset:52224
	ds_read_b128 v[198:201], v149 offset:53248
	ds_read_b128 v[202:205], v149 offset:54272
	ds_read_b128 v[206:209], v149 offset:55296
	ds_read_b128 v[210:213], v149 offset:56320
	global_load_lds_dwordx4 v130, s[98:99]
	s_add_i32 m0, s24, 0x2000
	s_add_u32 s22, s22, 0x40080
	s_addc_u32 s23, s23, 0
	s_add_i32 s24, s52, s38
	global_load_lds_dwordx4 v132, s[98:99]
	s_mov_b32 m0, s24
	s_nop 0
	global_load_lds_dwordx4 v130, s[22:23]
	s_add_i32 m0, s24, 0x2000
	s_nop 0
	global_load_lds_dwordx4 v132, s[22:23]
	s_mov_b32 m0, s42
	s_nop 0
	global_load_lds_dwordx4 v130, s[100:101]
	s_mov_b32 m0, s43
	s_nop 0
	global_load_lds_dwordx4 v132, s[100:101]
	s_waitcnt vmcnt(8)
	s_waitcnt lgkmcnt(0)
	s_barrier
	s_setprio 1
	s_waitcnt lgkmcnt(0)
	v_mfma_f32_16x16x32_bf16 v[62:65], v[150:153], v[182:185], v[62:65]
	v_mfma_f32_16x16x32_bf16 v[58:61], v[158:161], v[182:185], v[58:61]
	v_mfma_f32_16x16x32_bf16 v[50:53], v[150:153], v[190:193], v[50:53]
	v_mfma_f32_16x16x32_bf16 v[42:45], v[158:161], v[190:193], v[42:45]
	v_mfma_f32_16x16x32_bf16 v[34:37], v[150:153], v[198:201], v[34:37]
	v_mfma_f32_16x16x32_bf16 v[26:29], v[158:161], v[198:201], v[26:29]
	v_mfma_f32_16x16x32_bf16 v[18:21], v[150:153], v[206:209], v[18:21]
	v_mfma_f32_16x16x32_bf16 v[10:13], v[158:161], v[206:209], v[10:13]
	v_mfma_f32_16x16x32_bf16 v[62:65], v[154:157], v[186:189], v[62:65]
	v_mfma_f32_16x16x32_bf16 v[58:61], v[162:165], v[186:189], v[58:61]
	v_mfma_f32_16x16x32_bf16 v[50:53], v[154:157], v[194:197], v[50:53]
	v_mfma_f32_16x16x32_bf16 v[42:45], v[162:165], v[194:197], v[42:45]
	v_mfma_f32_16x16x32_bf16 v[34:37], v[154:157], v[202:205], v[34:37]
	v_mfma_f32_16x16x32_bf16 v[26:29], v[162:165], v[202:205], v[26:29]
	v_mfma_f32_16x16x32_bf16 v[18:21], v[154:157], v[210:213], v[18:21]
	v_mfma_f32_16x16x32_bf16 v[10:13], v[162:165], v[210:213], v[10:13]
	s_setprio 0
	s_setprio 1
	v_mfma_f32_16x16x32_bf16 v[54:57], v[166:169], v[182:185], v[54:57]
	v_mfma_f32_16x16x32_bf16 v[46:49], v[174:177], v[182:185], v[46:49]
	v_mfma_f32_16x16x32_bf16 v[38:41], v[166:169], v[190:193], v[38:41]
	v_mfma_f32_16x16x32_bf16 v[30:33], v[174:177], v[190:193], v[30:33]
	v_mfma_f32_16x16x32_bf16 v[22:25], v[166:169], v[198:201], v[22:25]
	v_mfma_f32_16x16x32_bf16 v[14:17], v[174:177], v[198:201], v[14:17]
	v_mfma_f32_16x16x32_bf16 v[6:9], v[166:169], v[206:209], v[6:9]
	v_mfma_f32_16x16x32_bf16 v[2:5], v[174:177], v[206:209], v[2:5]
	v_mfma_f32_16x16x32_bf16 v[54:57], v[170:173], v[186:189], v[54:57]
	v_mfma_f32_16x16x32_bf16 v[46:49], v[178:181], v[186:189], v[46:49]
	v_mfma_f32_16x16x32_bf16 v[38:41], v[170:173], v[194:197], v[38:41]
	v_mfma_f32_16x16x32_bf16 v[30:33], v[178:181], v[194:197], v[30:33]
	v_mfma_f32_16x16x32_bf16 v[22:25], v[170:173], v[202:205], v[22:25]
	v_mfma_f32_16x16x32_bf16 v[14:17], v[178:181], v[202:205], v[14:17]
	v_mfma_f32_16x16x32_bf16 v[6:9], v[170:173], v[210:213], v[6:9]
	s_barrier
	v_mfma_f32_16x16x32_bf16 v[2:5], v[178:181], v[210:213], v[2:5]
	s_setprio 0
	s_add_i32 s50, s50, 2
	s_add_u32 s20, s20, 0x100
	s_addc_u32 s21, s21, 0
	s_cmp_gt_u32 s50, 13
	s_cbranch_scc0 .LBB0_968
	s_nop 0
	s_add_u32 s20, s48, 0xffffff00
	s_addc_u32 s21, s49, -1
	s_andn2_b64 vcc, exec, s[2:3]
	s_cbranch_vccnz .LBB0_959
	v_mov_b32_e32 v2, 0
	s_mov_b32 s6, s12
	s_mov_b32 s4, s14
	s_mov_b64 s[8:9], s[18:19]
	s_mov_b32 s44, s47
	v_mov_b32_e32 v3, v2
	v_mov_b32_e32 v4, v2
	v_mov_b32_e32 v5, v2
	v_mov_b32_e32 v6, v2
	v_mov_b32_e32 v7, v2
	v_mov_b32_e32 v8, v2
	v_mov_b32_e32 v9, v2
	v_mov_b32_e32 v14, v2
	v_mov_b32_e32 v15, v2
	v_mov_b32_e32 v16, v2
	v_mov_b32_e32 v17, v2
	v_mov_b32_e32 v22, v2
	v_mov_b32_e32 v23, v2
	v_mov_b32_e32 v24, v2
	v_mov_b32_e32 v25, v2
	v_mov_b32_e32 v30, v2
	v_mov_b32_e32 v31, v2
	v_mov_b32_e32 v32, v2
	v_mov_b32_e32 v33, v2
	v_mov_b32_e32 v38, v2
	v_mov_b32_e32 v39, v2
	v_mov_b32_e32 v40, v2
	v_mov_b32_e32 v41, v2
	v_mov_b32_e32 v46, v2
	v_mov_b32_e32 v47, v2
	v_mov_b32_e32 v48, v2
	v_mov_b32_e32 v49, v2
	v_mov_b32_e32 v54, v2
	v_mov_b32_e32 v55, v2
	v_mov_b32_e32 v56, v2
	v_mov_b32_e32 v57, v2
	v_mov_b32_e32 v10, v2
	v_mov_b32_e32 v11, v2
	v_mov_b32_e32 v12, v2
	v_mov_b32_e32 v13, v2
	v_mov_b32_e32 v18, v2
	v_mov_b32_e32 v19, v2
	v_mov_b32_e32 v20, v2
	v_mov_b32_e32 v21, v2
	v_mov_b32_e32 v26, v2
	v_mov_b32_e32 v27, v2
	v_mov_b32_e32 v28, v2
	v_mov_b32_e32 v29, v2
	v_mov_b32_e32 v34, v2
	v_mov_b32_e32 v35, v2
	v_mov_b32_e32 v36, v2
	v_mov_b32_e32 v37, v2
	v_mov_b32_e32 v42, v2
	v_mov_b32_e32 v43, v2
	v_mov_b32_e32 v44, v2
	v_mov_b32_e32 v45, v2
	v_mov_b32_e32 v50, v2
	v_mov_b32_e32 v51, v2
	v_mov_b32_e32 v52, v2
	v_mov_b32_e32 v53, v2
	v_mov_b32_e32 v58, v2
	v_mov_b32_e32 v59, v2
	v_mov_b32_e32 v60, v2
	v_mov_b32_e32 v61, v2
	v_mov_b32_e32 v62, v2
	v_mov_b32_e32 v63, v2
	v_mov_b32_e32 v64, v2
	v_mov_b32_e32 v65, v2
	v_mov_b32_e32 v66, v2
	v_mov_b32_e32 v67, v2
	v_mov_b32_e32 v68, v2
	v_mov_b32_e32 v69, v2
	v_mov_b32_e32 v70, v2
	v_mov_b32_e32 v71, v2
	v_mov_b32_e32 v72, v2
	v_mov_b32_e32 v73, v2
	v_mov_b32_e32 v78, v2
	v_mov_b32_e32 v79, v2
	v_mov_b32_e32 v80, v2
	v_mov_b32_e32 v81, v2
	v_mov_b32_e32 v86, v2
	v_mov_b32_e32 v87, v2
	v_mov_b32_e32 v88, v2
	v_mov_b32_e32 v89, v2
	v_mov_b32_e32 v94, v2
	v_mov_b32_e32 v95, v2
	v_mov_b32_e32 v96, v2
	v_mov_b32_e32 v97, v2
	v_mov_b32_e32 v102, v2
	v_mov_b32_e32 v103, v2
	v_mov_b32_e32 v104, v2
	v_mov_b32_e32 v105, v2
	v_mov_b32_e32 v110, v2
	v_mov_b32_e32 v111, v2
	v_mov_b32_e32 v112, v2
	v_mov_b32_e32 v113, v2
	v_mov_b32_e32 v118, v2
	v_mov_b32_e32 v119, v2
	v_mov_b32_e32 v120, v2
	v_mov_b32_e32 v121, v2
	v_mov_b32_e32 v74, v2
	v_mov_b32_e32 v75, v2
	v_mov_b32_e32 v76, v2
	v_mov_b32_e32 v77, v2
	v_mov_b32_e32 v82, v2
	v_mov_b32_e32 v83, v2
	v_mov_b32_e32 v84, v2
	v_mov_b32_e32 v85, v2
	v_mov_b32_e32 v90, v2
	v_mov_b32_e32 v91, v2
	v_mov_b32_e32 v92, v2
	v_mov_b32_e32 v93, v2
	v_mov_b32_e32 v98, v2
	v_mov_b32_e32 v99, v2
	v_mov_b32_e32 v100, v2
	v_mov_b32_e32 v101, v2
	v_mov_b32_e32 v106, v2
	v_mov_b32_e32 v107, v2
	v_mov_b32_e32 v108, v2
	v_mov_b32_e32 v109, v2
	v_mov_b32_e32 v114, v2
	v_mov_b32_e32 v115, v2
	v_mov_b32_e32 v116, v2
	v_mov_b32_e32 v117, v2
	v_mov_b32_e32 v122, v2
	v_mov_b32_e32 v123, v2
	v_mov_b32_e32 v124, v2
	v_mov_b32_e32 v125, v2
	v_mov_b32_e32 v126, v2
	v_mov_b32_e32 v127, v2
	v_mov_b32_e32 v128, v2
	v_mov_b32_e32 v129, v2
	s_andn2_b64 vcc, exec, s[0:1]
	s_cbranch_vccnz .LBB0_960
